# scan4 (8192-step) also two rows per thread with the same schedule
# speedup vs baseline: 1.0548x; 1.0032x over previous
; template <int KT>
; __device__ __forceinline__ void scan_block(const Ctx& C, const PV& P, int layer, int sq, int h, int d, int row0, unsigned char* smem) {
;     ...
;     const float* mu = P.inp(13) + (size_t)layer * 1920; const float* k_k = P.inp(19) + (size_t)layer * 512; const float* k_a = P.inp(20) + (size_t)layer * 512;
;     const int tid = C.tid, row = tid / TPR, q = tid % TPR;
;     const int lt0 = seqbase_of(sq), S = seqlen_of(sq);
;     const int ch = tid & 63, c = h * 64 + ch;
;     const float mu_r = mu[c], mu_k = mu[512 + c], kkw = k_k[c], kaw = k_a[c];
;     const int vr = (ROWS == 32) ? (tid & 31) : (tid & 63);
;     const int vcol = 1024 + h * 64 + row0 + vr; const float mu_v = mu[vcol];
;     const f16* wdec = wa + (size_t)d * SZ512; const f16* aact = wa + (size_t)(2 + d) * SZ512;
;     f16* ydst = yfb + (size_t)d * SZ512;
;     f32x2 s[KT / 2];
; #pragma unroll
;     for (int j = 0; j < KT / 2; ++j) s[j] = (f32x2){0.f, 0.f};
;     f16 pr_[2][3], pk_[2][3], pa_[2], pw_[2], pv_[NV][3]; float pn_[2];
;     auto prefetch = [&](int c0) {
; #pragma unroll
;         for (int j = 0; j < 2; ++j) {
;             const int i = (tid >> 6) + 8 * j, tstep = c0 + i, t = d == 0 ? tstep : S - 1 - tstep, lt = lt0 + t;
;             const int tm = t > 0 ? lt - 1 : lt, tp = t < S - 1 ? lt + 1 : lt;
;             pr_[j][0] = raw[(size_t)tm * 1920 + c]; pr_[j][1] = raw[(size_t)lt * 1920 + c]; pr_[j][2] = raw[(size_t)tp * 1920 + c];
;             pk_[j][0] = raw[(size_t)tm * 1920 + 512 + c]; pk_[j][1] = raw[(size_t)lt * 1920 + 512 + c]; pk_[j][2] = raw[(size_t)tp * 1920 + 512 + c];
;             pa_[j] = aact[(size_t)lt * 512 + c]; pw_[j] = wdec[(size_t)lt * 512 + c]; pn_[j] = invn[(size_t)lt * 8 + h];
.LBB0_543:
	s_load_dwordx2 s[6:7], s[24:25], 0x68
	s_load_dwordx4 s[40:43], s[24:25], 0x98
	s_lshl_b32 s4, s87, 5
	v_readlane_b32 s12, v255, 26
	s_ashr_i32 s2, s87, 2
	s_bfe_u32 s3, s87, 0x10001
	s_and_b32 s5, s4, 32
	s_mul_i32 s8, s12, 0x1e00
	v_readlane_b32 s13, v255, 27
	s_mul_hi_i32 s4, s12, 0x1e00
	s_waitcnt lgkmcnt(0)
	s_add_u32 s6, s6, s8
	s_addc_u32 s7, s7, s4
	s_lshl_b64 s[8:9], s[12:13], 11
	s_add_u32 s16, s40, s8
	s_addc_u32 s17, s41, s9
	s_add_u32 s8, s42, s8
	s_addc_u32 s9, s43, s9
	v_and_b32_e32 v18, 63, v199
	s_lshl_b32 s12, s2, 6
	v_or_b32_e32 v0, s12, v18
	v_ashrrev_i32_e32 v1, 31, v0
	v_lshlrev_b64 v[2:3], 2, v[0:1]
	v_lshl_add_u64 v[4:5], s[6:7], 0, v[2:3]
	global_load_dword v54, v[4:5], off
	global_load_dword v55, v[4:5], off offset:2048
	v_lshl_add_u64 v[4:5], s[16:17], 0, v[2:3]
	v_lshl_add_u64 v[2:3], s[8:9], 0, v[2:3]
	v_and_b32_e32 v19, 31, v199
	global_load_dword v57, v[2:3], off
	v_or_b32_e32 v2, s12, v19
	v_or_b32_e32 v2, s5, v2
	v_add_u32_e32 v2, 0x400, v2
	s_mul_i32 s4, s3, 0x2800000
	v_ashrrev_i32_e32 v3, 31, v2
	s_add_u32 s20, s66, s4
	global_load_dword v56, v[4:5], off
	v_lshl_add_u64 v[4:5], v[2:3], 2, s[6:7]
	s_addc_u32 s21, s67, 0
	v_lshlrev_b64 v[0:1], 1, v[0:1]
	global_load_dword v58, v[4:5], off
	v_ashrrev_i32_e32 v59, 6, v144
	s_cmp_eq_u32 s3, 0
	v_lshl_add_u64 v[4:5], s[20:21], 0, v[0:1]
	s_mov_b64 s[6:7], 0x1c58c000
	v_sub_u32_e32 v6, 0x1fff, v59
	s_cselect_b64 s[40:41], -1, 0
	v_lshl_add_u64 v[36:37], v[4:5], 0, s[6:7]
	s_mov_b64 s[6:7], 0x1758c000
	v_lshl_add_u64 v[38:39], v[4:5], 0, s[6:7]
	v_cndmask_b32_e64 v4, v6, v59, s[40:41]
	v_cmp_lt_i32_e32 vcc, 0, v4
	v_mov_b64_e32 v[6:7], s[14:15]
	v_mad_i64_i32 v[10:11], s[6:7], v4, s77, v[6:7]
	v_subbrev_co_u32_e64 v5, s[42:43], 0, v4, vcc
	v_cmp_gt_i32_e64 s[42:43], s18, v4
	v_mad_i64_i32 v[8:9], s[6:7], v5, s77, v[6:7]
	s_nop 0
	v_addc_co_u32_e64 v12, s[44:45], 0, v4, s[42:43]
	v_ashrrev_i32_e32 v5, 31, v4
	v_lshl_add_u64 v[8:9], v[8:9], 0, v[0:1]
	v_mad_i64_i32 v[12:13], s[6:7], v12, s77, v[6:7]
	v_lshlrev_b64 v[14:15], 10, v[4:5]
	s_waitcnt vmcnt(0)
	s_barrier
; template <int KT>
; __device__ __forceinline__ void scan_block(const Ctx& C, const PV& P, int layer, int sq, int h, int d, int row0, unsigned char* smem) {
;     ...
;     f32x2 s[KT / 2];
; #pragma unroll
;     for (int j = 0; j < KT / 2; ++j) s[j] = (f32x2){0.f, 0.f};
;     f16 pr_[2][3], pk_[2][3], pa_[2], pw_[2], pv_[NV][3]; float pn_[2];
;     auto prefetch = [&](int c0) {
; #pragma unroll
;         for (int j = 0; j < 2; ++j) {
;             const int i = (tid >> 6) + 8 * j, tstep = c0 + i, t = d == 0 ? tstep : S - 1 - tstep, lt = lt0 + t;
;             const int tm = t > 0 ? lt - 1 : lt, tp = t < S - 1 ? lt + 1 : lt;
;             pr_[j][0] = raw[(size_t)tm * 1920 + c]; pr_[j][1] = raw[(size_t)lt * 1920 + c]; pr_[j][2] = raw[(size_t)tp * 1920 + c];
;             pk_[j][0] = raw[(size_t)tm * 1920 + 512 + c]; pk_[j][1] = raw[(size_t)lt * 1920 + 512 + c]; pk_[j][2] = raw[(size_t)tp * 1920 + 512 + c];
;             pa_[j] = aact[(size_t)lt * 512 + c]; pw_[j] = wdec[(size_t)lt * 512 + c]; pn_[j] = invn[(size_t)lt * 8 + h];
;         }
; #pragma unroll
;         for (int j = 0; j < NV; ++j) {
;             const int i = (ROWS == 32) ? (tid >> 5) : ((tid >> 6) + 8 * j), tstep = c0 + i, t = d == 0 ? tstep : S - 1 - tstep, lt = lt0 + t;
;             const int tm = t > 0 ? lt - 1 : lt, tp = t < S - 1 ? lt + 1 : lt;
;             pv_[j][0] = raw[(size_t)tm * 1920 + vcol]; pv_[j][1] = raw[(size_t)lt * 1920 + vcol]; pv_[j][2] = raw[(size_t)tp * 1920 + vcol];
;         }
;     };
;     auto stage = [&](int c0, unsigned char* buf) {
;         float* vec = (float*)buf; float* vbuf = (float*)(buf + 20480);
; #pragma unroll
;         for (int j = 0; j < 2; ++j) {
;             const int i = (tid >> 6) + 8 * j, tstep = c0 + i, t = d == 0 ? tstep : S - 1 - tstep;
;             const float rm = t > 0 ? (float)pr_[j][0] : 0.f, rp = t < S - 1 ? (float)pr_[j][2] : 0.f, km = t > 0 ? (float)pk_[j][0] : 0.f, kp = t < S - 1 ? (float)pk_[j][2] : 0.f;
;             const float r1 = (float)pr_[j][1], k1 = (float)pk_[j][1];
;             const float r = r1 + (0.5f * (rm + rp) - r1) * mu_r;
;             const float k = k1 + (0.5f * (km + kp) - k1) * mu_k;
;             const float kk = k * kkw * pn_[j], a = (float)pa_[j];
;             vec[(0 * CH + i) * 64 + ch] = kk;
;             vec[(1 * CH + i) * 64 + ch] = (float)pw_[j];
;             vec[(2 * CH + i) * 64 + ch] = kk * a;
	v_lshl_add_u64 v[10:11], v[10:11], 0, v[0:1]
	v_lshl_add_u64 v[12:13], v[12:13], 0, v[0:1]
	v_lshl_add_u64 v[16:17], v[36:37], 0, v[14:15]
	v_lshl_add_u64 v[14:15], v[38:39], 0, v[14:15]
	global_load_ushort v60, v[8:9], off
	global_load_ushort v61, v[10:11], off
	global_load_ushort v62, v[12:13], off
	global_load_ushort v63, v[12:13], off offset:1024
	global_load_ushort v66, v[16:17], off
	global_load_ushort v68, v[14:15], off
	global_load_ushort v64, v[10:11], off offset:1024
	global_load_ushort v65, v[8:9], off offset:1024
	s_ashr_i32 s3, s2, 31
	s_lshl_b64 s[2:3], s[2:3], 2
	s_add_u32 s2, s66, s2
	s_addc_u32 s3, s67, s3
	s_add_u32 s2, s2, 0x3f58c000
	s_addc_u32 s3, s3, 0
	v_lshlrev_b64 v[4:5], 5, v[4:5]
	v_lshl_add_u64 v[4:5], s[2:3], 0, v[4:5]
	global_load_dword v73, v[4:5], off
	v_add_u32_e32 v20, 8, v59
	v_sub_u32_e32 v4, 0x1ff7, v59
	v_cndmask_b32_e64 v4, v4, v20, s[40:41]
	v_cmp_lt_i32_e64 s[44:45], 0, v4
	v_mad_i64_i32 v[10:11], s[6:7], v4, s77, v[6:7]
	s_nop 0
	v_subbrev_co_u32_e64 v5, s[46:47], 0, v4, s[44:45]
	v_cmp_gt_i32_e64 s[46:47], s18, v4
	v_mad_i64_i32 v[8:9], s[6:7], v5, s77, v[6:7]
	s_nop 0
	v_addc_co_u32_e64 v12, s[48:49], 0, v4, s[46:47]
	v_ashrrev_i32_e32 v5, 31, v4
	v_lshl_add_u64 v[8:9], v[8:9], 0, v[0:1]
	v_mad_i64_i32 v[12:13], s[6:7], v12, s77, v[6:7]
	v_lshlrev_b64 v[14:15], 10, v[4:5]
	v_lshl_add_u64 v[10:11], v[10:11], 0, v[0:1]
	v_lshl_add_u64 v[12:13], v[12:13], 0, v[0:1]
	v_lshl_add_u64 v[16:17], v[36:37], 0, v[14:15]
	global_load_ushort v75, v[8:9], off
	global_load_ushort v76, v[12:13], off
	global_load_ushort v79, v[12:13], off offset:1024
	global_load_ushort v86, v[16:17], off
	global_load_ushort v80, v[10:11], off offset:1024
	global_load_ushort v81, v[8:9], off offset:1024
	global_load_ushort v77, v[10:11], off
	v_ashrrev_i32_e32 v67, 5, v144
	v_sub_u32_e32 v69, 0x1fff, v67
	v_lshl_add_u64 v[8:9], v[38:39], 0, v[14:15]
	v_lshlrev_b64 v[4:5], 5, v[4:5]
	v_cndmask_b32_e64 v10, v69, v67, s[40:41]
	v_lshl_add_u64 v[4:5], s[2:3], 0, v[4:5]
	global_load_ushort v87, v[8:9], off
	global_load_dword v89, v[4:5], off
	v_cmp_lt_i32_e64 s[48:49], 0, v10
	v_lshlrev_b64 v[2:3], 1, v[2:3]
	v_bfi_b32 v74, 63, v199, v144
	v_subbrev_co_u32_e64 v4, s[50:51], 0, v10, s[48:49]
	v_cmp_gt_i32_e64 s[50:51], s18, v10
	v_mad_i64_i32 v[4:5], s[6:7], v4, s77, v[6:7]
	s_nop 0
	v_addc_co_u32_e64 v8, s[52:53], 0, v10, s[50:51]
	v_lshl_add_u64 v[4:5], v[4:5], 0, v[2:3]
	v_mad_i64_i32 v[8:9], s[6:7], v8, s77, v[6:7]
	v_lshl_add_u64 v[8:9], v[8:9], 0, v[2:3]
	global_load_ushort v90, v[4:5], off
	global_load_ushort v92, v[8:9], off
	v_mad_i64_i32 v[4:5], s[6:7], v10, s77, v[6:7]
	v_lshl_add_u64 v[4:5], v[4:5], 0, v[2:3]
	global_load_ushort v91, v[4:5], off
	v_lshrrev_b32_e32 v4, 28, v145
	v_add_u32_e32 v4, v144, v4
	v_ashrrev_i32_e32 v70, 4, v4
	v_and_b32_e32 v71, -16, v4
	v_lshl_add_u32 v8, v144, 2, 0
	v_lshl_add_u32 v9, v74, 2, 0
	v_lshl_or_b32 v78, v20, 6, v18
	s_ashr_i32 s13, s12, 31
	s_lshl_b64 s[6:7], s[12:13], 1
	s_add_u32 s6, s20, s6
	v_lshl_or_b32 v82, v67, 6, v19
	s_addc_u32 s7, s21, s7
	s_lshl_b32 s5, s5, 1
	v_sub_u32_e32 v72, v144, v71
	s_add_u32 s6, s6, s5
	s_waitcnt vmcnt(20)
	v_cvt_f32_f16_e32 v4, v60
	s_addc_u32 s7, s7, 0
	s_waitcnt vmcnt(18)
	v_cvt_f32_f16_e32 v5, v62
	s_waitcnt vmcnt(17)
	v_cvt_f32_f16_e32 v7, v63
	v_cndmask_b32_e32 v4, 0, v4, vcc
	v_lshlrev_b32_e32 v132, 1, v19
	v_cndmask_b32_e64 v5, 0, v5, s[42:43]
	s_waitcnt vmcnt(13)
	v_cvt_f32_f16_e32 v6, v65
	v_cndmask_b32_e64 v7, 0, v7, s[42:43]
	v_add_f32_e32 v4, v4, v5
	v_fma_mix_f32 v4, v4, s38, -v61 op_sel_hi:[0,0,1]
	v_cndmask_b32_e32 v6, 0, v6, vcc
	v_add_f32_e32 v5, v6, v7
	v_fma_mix_f32 v5, v5, s38, -v64 op_sel_hi:[0,0,1]
	v_fma_mix_f32 v5, v55, v5, v64 op_sel_hi:[0,0,1]
	v_mul_f32_e32 v6, v56, v5
	s_waitcnt vmcnt(12)
	v_mul_f32_e32 v6, v73, v6
	v_cvt_f32_f16_e32 v7, v66
	ds_write_b32 v8, v6
	v_cvt_f32_f16_e32 v8, v68
	v_fma_mix_f32 v4, v54, v4, v61 op_sel_hi:[0,0,1]
	v_mul_f32_e32 v6, v6, v7
	v_lshl_add_u64 v[42:43], s[14:15], 0, v[0:1]
	ds_write2st64_b32 v9, v8, v6 offset0:16 offset1:32
	v_add_f32_e32 v6, -1.0, v7
	v_fma_f32 v6, v57, v6, 1.0
	v_mul_f32_e32 v5, v6, v5
	ds_write2st64_b32 v9, v5, v4 offset0:48 offset1:64
	v_lshl_add_u32 v9, v78, 2, 0
	v_mov_b32_e32 v0, 0
	s_mov_b32 s4, 0
	v_lshlrev_b32_e32 v83, 4, v72
	s_waitcnt vmcnt(11)
	v_cvt_f32_f16_e32 v4, v75
	s_waitcnt vmcnt(10)
	v_cvt_f32_f16_e32 v5, v76
	s_waitcnt vmcnt(9)
	v_cvt_f32_f16_e32 v7, v79
	s_waitcnt vmcnt(8)
	v_cvt_f32_f16_e32 v8, v86
	v_cndmask_b32_e64 v4, 0, v4, s[44:45]
	s_waitcnt vmcnt(6)
	v_cvt_f32_f16_e32 v6, v81
	v_cndmask_b32_e64 v5, 0, v5, s[46:47]
	v_cndmask_b32_e64 v7, 0, v7, s[46:47]
	v_add_f32_e32 v4, v4, v5
	v_cndmask_b32_e64 v6, 0, v6, s[44:45]
	v_add_f32_e32 v5, v6, v7
	v_fma_mix_f32 v5, v5, s38, -v80 op_sel_hi:[0,0,1]
	s_waitcnt vmcnt(4)
	v_cvt_f32_f16_e32 v7, v87
	v_fma_mix_f32 v5, v55, v5, v80 op_sel_hi:[0,0,1]
	v_mul_f32_e32 v6, v56, v5
	s_waitcnt vmcnt(3)
	v_mul_f32_e32 v6, v89, v6
	ds_write2st64_b32 v9, v6, v7 offset1:16
	v_add_f32_e32 v7, -1.0, v8
	v_fma_f32 v7, v57, v7, 1.0
	v_mul_f32_e32 v6, v6, v8
	v_mul_f32_e32 v5, v7, v5
	v_fma_mix_f32 v4, v4, s38, -v77 op_sel_hi:[0,0,1]
	v_fma_mix_f32 v4, v54, v4, v77 op_sel_hi:[0,0,1]
	ds_write2st64_b32 v9, v6, v5 offset0:32 offset1:48
	ds_write_b32 v9, v4 offset:16384
	v_lshl_add_u32 v6, v82, 2, 0
	v_lshlrev_b32_e32 v84, 9, v67
	v_lshlrev_b32_e32 v85, 4, v19
	s_waitcnt vmcnt(2)
	v_cvt_f32_f16_e32 v7, v90
	s_waitcnt vmcnt(1)
	v_cvt_f32_f16_e32 v8, v92
	v_lshl_add_u64 v[44:45], s[14:15], 0, v[2:3]
	v_sub_u32_e32 v88, 0x1fe7, v59
	v_cndmask_b32_e64 v4, 0, v7, s[48:49]
	v_cndmask_b32_e64 v5, 0, v8, s[50:51]
	v_add_f32_e32 v4, v4, v5
	s_waitcnt vmcnt(0)
	v_fma_mix_f32 v4, v4, s38, -v91 op_sel_hi:[0,0,1]
	v_fma_mix_f32 v4, v58, v4, v91 op_sel_hi:[0,0,1]
	ds_write_b32 v6, v4 offset:20480
	v_and_b32_e32 v4, 3, v72
	v_cmp_eq_u32_e64 s[42:43], 0, v4
	v_lshl_add_u64 v[4:5], s[6:7], 0, v[132:133]
	s_mov_b64 s[6:7], 0x2b58c000
	v_lshl_add_u64 v[40:41], v[4:5], 0, s[6:7]
	s_mov_b32 s5, 0x8000
	v_mov_b32_e32 v1, v0
	v_mov_b32_e32 v2, v0
	v_mov_b32_e32 v3, v0
	v_mov_b32_e32 v204, v0
	v_mov_b32_e32 v205, v0
	v_mov_b32_e32 v206, v0
	v_mov_b32_e32 v207, v0
	s_waitcnt lgkmcnt(0)
	s_barrier
	s_branch .LBB0_545

; template <int KT>
; __device__ __forceinline__ void scan_block(const Ctx& C, const PV& P, int layer, int sq, int h, int d, int row0, unsigned char* smem) {
;     ...
;         unsigned char* buf = smem + (cix & 1) * 32768;
;         if (cix + 1 < nch) prefetch((cix + 1) * CH);
;         {
;             const float* vec = (const float*)buf; const float* vbuf = (const float*)(buf + 20480); float* ybuf = (float*)(buf + 24576);
;             const f32x4* vp0 = (const f32x4*)(vec + q * KT);
;             f32x4 nx[5][KT / 4]; float nvv;
; #pragma unroll
;             for (int u = 0; u < KT / 4; ++u)
; #pragma unroll
;                 for (int a5 = 0; a5 < 5; ++a5) nx[a5][u] = vp0[a5 * CH * 16 + u];
;             nvv = vbuf[row];
;             float yv[CH];
; #pragma unroll
;             for (int i = 0; i < CH; ++i) {
;                 f32x2 kk2[KT / 2], w2[KT / 2], b2[KT / 2], kd2[KT / 2], r2[KT / 2];
; #pragma unroll
;                 for (int u = 0; u < KT / 4; ++u) {
;                     kk2[2 * u] = (f32x2){nx[0][u][0], nx[0][u][1]}; kk2[2 * u + 1] = (f32x2){nx[0][u][2], nx[0][u][3]};
;                     w2[2 * u] = (f32x2){nx[1][u][0], nx[1][u][1]}; w2[2 * u + 1] = (f32x2){nx[1][u][2], nx[1][u][3]};
;                     b2[2 * u] = (f32x2){nx[2][u][0], nx[2][u][1]}; b2[2 * u + 1] = (f32x2){nx[2][u][2], nx[2][u][3]};
;                     kd2[2 * u] = (f32x2){nx[3][u][0], nx[3][u][1]}; kd2[2 * u + 1] = (f32x2){nx[3][u][2], nx[3][u][3]};
;                     r2[2 * u] = (f32x2){nx[4][u][0], nx[4][u][1]}; r2[2 * u + 1] = (f32x2){nx[4][u][2], nx[4][u][3]};
;                 }
;                 const float vv = nvv;
;                 if (i + 1 < CH) {
; #pragma unroll
;                     for (int u = 0; u < KT / 4; ++u)
; #pragma unroll
;                         for (int a5 = 0; a5 < 5; ++a5) nx[a5][u] = vp0[(i + 1) * 16 + a5 * CH * 16 + u];
;                     nvv = vbuf[(i + 1) * 64 + row];
;                 }
;                 f32x2 acc2 = s[0] * kk2[0];
; #pragma unroll
;                 for (int j = 1; j < KT / 2; ++j) acc2 = __builtin_elementwise_fma(s[j], kk2[j], acc2);
;                 float sa = acc2[0] + acc2[1];
;                 sa += dppf<0xB1>(sa); sa += dppf<0x4E>(sa); sa += dppf<0x141>(sa);
;                 if (TPR == 16) sa += dppf<0x140>(sa);
;                 sa = -sa;
.LBB0_547:
	s_add_i32 s6, s5, 0xffff8000
	s_and_b32 s6, s6, 0x8000
	s_add_i32 s6, s6, 0
	s_cmpk_ge_u32 s27, 0x100
	s_cbranch_scc1 .Lsc4_skip
	v_add_u32_e32 v200, s6, v83
	v_lshl_add_u32 v201, v70, 2, s6
	v_add_u32_e32 v203, 64, v201
	v_and_b32_e32 v202, 12, v72
	v_add3_u32 v202, s6, v71, v202
	ds_read2st64_b32 v[186:187], v201 offset0:80 offset1:81
	ds_read2st64_b32 v[190:191], v203 offset0:80 offset1:81
	ds_read_b128 v[4:7], v200
	ds_read_b128 v[16:19], v200 offset:12288
	ds_read_b128 v[12:15], v200 offset:8192
	ds_read_b128 v[8:11], v200 offset:4096
	ds_read_b128 v[20:23], v200 offset:16384
	s_waitcnt lgkmcnt(0)
	ds_read_b128 v[24:27], v200 offset:256
	ds_read_b128 v[48:51], v200 offset:12544
	ds_read_b128 v[32:35], v200 offset:8448
	ds_read_b128 v[28:31], v200 offset:4352
	ds_read_b128 v[100:103], v200 offset:16640
	v_pk_mul_f32 v[104:105], v[0:1], v[4:5]
	v_pk_mul_f32 v[106:107], v[204:205], v[4:5]
	v_pk_fma_f32 v[104:105], v[2:3], v[6:7], v[104:105]
	v_pk_fma_f32 v[106:107], v[206:207], v[6:7], v[106:107]
	v_add_f32_e32 v108, v104, v105
	v_add_f32_e32 v110, v106, v107
	v_pk_mul_f32 v[112:113], v[16:17], v[186:187] op_sel_hi:[1,0]
	v_add_f32_dpp v108, v108, v108 quad_perm:[1,0,3,2] row_mask:0xf bank_mask:0xf bound_ctrl:1
	v_add_f32_dpp v110, v110, v110 quad_perm:[1,0,3,2] row_mask:0xf bank_mask:0xf bound_ctrl:1
	v_pk_mul_f32 v[116:117], v[16:17], v[190:191] op_sel_hi:[1,0]
	v_add_f32_dpp v108, v108, v108 quad_perm:[2,3,0,1] row_mask:0xf bank_mask:0xf bound_ctrl:1
	v_add_f32_dpp v110, v110, v110 quad_perm:[2,3,0,1] row_mask:0xf bank_mask:0xf bound_ctrl:1
	v_pk_mul_f32 v[114:115], v[18:19], v[186:187] op_sel_hi:[1,0]
	v_add_f32_dpp v108, v108, v108 row_half_mirror row_mask:0xf bank_mask:0xf bound_ctrl:1
	v_add_f32_dpp v110, v110, v110 row_half_mirror row_mask:0xf bank_mask:0xf bound_ctrl:1
	v_pk_mul_f32 v[118:119], v[18:19], v[190:191] op_sel_hi:[1,0]
	v_add_f32_dpp v108, v108, v108 row_mirror row_mask:0xf bank_mask:0xf bound_ctrl:1
	v_add_f32_dpp v110, v110, v110 row_mirror row_mask:0xf bank_mask:0xf bound_ctrl:1
	v_pk_fma_f32 v[112:113], v[108:109], v[12:13], v[112:113] op_sel_hi:[0,1,1] neg_lo:[1,0,0] neg_hi:[1,0,0]
	v_pk_fma_f32 v[116:117], v[110:111], v[12:13], v[116:117] op_sel_hi:[0,1,1] neg_lo:[1,0,0] neg_hi:[1,0,0]
	v_pk_fma_f32 v[114:115], v[108:109], v[14:15], v[114:115] op_sel_hi:[0,1,1] neg_lo:[1,0,0] neg_hi:[1,0,0]
	v_pk_fma_f32 v[118:119], v[110:111], v[14:15], v[118:119] op_sel_hi:[0,1,1] neg_lo:[1,0,0] neg_hi:[1,0,0]
	v_pk_fma_f32 v[0:1], v[0:1], v[8:9], v[112:113]
	v_pk_fma_f32 v[204:205], v[204:205], v[8:9], v[116:117]
	v_pk_fma_f32 v[2:3], v[2:3], v[10:11], v[114:115]
	v_pk_fma_f32 v[206:207], v[206:207], v[10:11], v[118:119]
	v_pk_fma_f32 v[120:121], v[0:1], v[20:21], 0 op_sel_hi:[1,1,0]
	v_pk_fma_f32 v[122:123], v[204:205], v[20:21], 0 op_sel_hi:[1,1,0]
	v_pk_fma_f32 v[120:121], v[2:3], v[22:23], v[120:121]
	v_pk_fma_f32 v[122:123], v[206:207], v[22:23], v[122:123]
	v_add_f32_e32 v124, v120, v121
	v_add_f32_e32 v125, v122, v123
	s_waitcnt lgkmcnt(0)
	v_add_f32_dpp v124, v124, v124 quad_perm:[1,0,3,2] row_mask:0xf bank_mask:0xf bound_ctrl:1
	v_add_f32_dpp v125, v125, v125 quad_perm:[1,0,3,2] row_mask:0xf bank_mask:0xf bound_ctrl:1
	ds_read2st64_b32 v[188:189], v201 offset0:82 offset1:83
	v_add_f32_dpp v124, v124, v124 quad_perm:[2,3,0,1] row_mask:0xf bank_mask:0xf bound_ctrl:1
	v_add_f32_dpp v125, v125, v125 quad_perm:[2,3,0,1] row_mask:0xf bank_mask:0xf bound_ctrl:1
	ds_write2st64_b32 v202, v124, v125 offset0:96 offset1:97
	ds_read2st64_b32 v[192:193], v203 offset0:82 offset1:83
	ds_read_b128 v[4:7], v200 offset:512
	ds_read_b128 v[16:19], v200 offset:12800
	ds_read_b128 v[12:15], v200 offset:8704
	ds_read_b128 v[8:11], v200 offset:4608
	ds_read_b128 v[20:23], v200 offset:16896
	v_pk_mul_f32 v[104:105], v[0:1], v[24:25]
	v_pk_mul_f32 v[106:107], v[204:205], v[24:25]
	v_pk_fma_f32 v[104:105], v[2:3], v[26:27], v[104:105]
	v_pk_fma_f32 v[106:107], v[206:207], v[26:27], v[106:107]
	v_add_f32_e32 v108, v104, v105
	v_add_f32_e32 v110, v106, v107
	v_pk_mul_f32 v[112:113], v[48:49], v[186:187] op_sel:[0,1] op_sel_hi:[1,1]
	v_add_f32_dpp v108, v108, v108 quad_perm:[1,0,3,2] row_mask:0xf bank_mask:0xf bound_ctrl:1
	v_add_f32_dpp v110, v110, v110 quad_perm:[1,0,3,2] row_mask:0xf bank_mask:0xf bound_ctrl:1
	v_pk_mul_f32 v[116:117], v[48:49], v[190:191] op_sel:[0,1] op_sel_hi:[1,1]
	v_add_f32_dpp v108, v108, v108 quad_perm:[2,3,0,1] row_mask:0xf bank_mask:0xf bound_ctrl:1
	v_add_f32_dpp v110, v110, v110 quad_perm:[2,3,0,1] row_mask:0xf bank_mask:0xf bound_ctrl:1
	v_pk_mul_f32 v[114:115], v[50:51], v[186:187] op_sel:[0,1] op_sel_hi:[1,1]
	v_add_f32_dpp v108, v108, v108 row_half_mirror row_mask:0xf bank_mask:0xf bound_ctrl:1
	v_add_f32_dpp v110, v110, v110 row_half_mirror row_mask:0xf bank_mask:0xf bound_ctrl:1
	v_pk_mul_f32 v[118:119], v[50:51], v[190:191] op_sel:[0,1] op_sel_hi:[1,1]
	v_add_f32_dpp v108, v108, v108 row_mirror row_mask:0xf bank_mask:0xf bound_ctrl:1
	v_add_f32_dpp v110, v110, v110 row_mirror row_mask:0xf bank_mask:0xf bound_ctrl:1
	v_pk_fma_f32 v[112:113], v[108:109], v[32:33], v[112:113] op_sel_hi:[0,1,1] neg_lo:[1,0,0] neg_hi:[1,0,0]
	v_pk_fma_f32 v[116:117], v[110:111], v[32:33], v[116:117] op_sel_hi:[0,1,1] neg_lo:[1,0,0] neg_hi:[1,0,0]
	v_pk_fma_f32 v[114:115], v[108:109], v[34:35], v[114:115] op_sel_hi:[0,1,1] neg_lo:[1,0,0] neg_hi:[1,0,0]
	v_pk_fma_f32 v[118:119], v[110:111], v[34:35], v[118:119] op_sel_hi:[0,1,1] neg_lo:[1,0,0] neg_hi:[1,0,0]
	v_pk_fma_f32 v[0:1], v[0:1], v[28:29], v[112:113]
	v_pk_fma_f32 v[204:205], v[204:205], v[28:29], v[116:117]
	v_pk_fma_f32 v[2:3], v[2:3], v[30:31], v[114:115]
	v_pk_fma_f32 v[206:207], v[206:207], v[30:31], v[118:119]
	v_pk_fma_f32 v[120:121], v[0:1], v[100:101], 0 op_sel_hi:[1,1,0]
	v_pk_fma_f32 v[122:123], v[204:205], v[100:101], 0 op_sel_hi:[1,1,0]
	v_pk_fma_f32 v[120:121], v[2:3], v[102:103], v[120:121]
	v_pk_fma_f32 v[122:123], v[206:207], v[102:103], v[122:123]
	v_add_f32_e32 v124, v120, v121
	v_add_f32_e32 v125, v122, v123
	s_waitcnt lgkmcnt(0)
; template <int KT>
; __device__ __forceinline__ void scan_block(const Ctx& C, const PV& P, int layer, int sq, int h, int d, int row0, unsigned char* smem) {
;     ...
;             for (int i = 0; i < CH; ++i) {
;                 f32x2 kk2[KT / 2], w2[KT / 2], b2[KT / 2], kd2[KT / 2], r2[KT / 2];
; #pragma unroll
;                 for (int u = 0; u < KT / 4; ++u) {
;                     kk2[2 * u] = (f32x2){nx[0][u][0], nx[0][u][1]}; kk2[2 * u + 1] = (f32x2){nx[0][u][2], nx[0][u][3]};
;                     w2[2 * u] = (f32x2){nx[1][u][0], nx[1][u][1]}; w2[2 * u + 1] = (f32x2){nx[1][u][2], nx[1][u][3]};
;                     b2[2 * u] = (f32x2){nx[2][u][0], nx[2][u][1]}; b2[2 * u + 1] = (f32x2){nx[2][u][2], nx[2][u][3]};
;                     kd2[2 * u] = (f32x2){nx[3][u][0], nx[3][u][1]}; kd2[2 * u + 1] = (f32x2){nx[3][u][2], nx[3][u][3]};
;                     r2[2 * u] = (f32x2){nx[4][u][0], nx[4][u][1]}; r2[2 * u + 1] = (f32x2){nx[4][u][2], nx[4][u][3]};
;                 }
;                 const float vv = nvv;
;                 if (i + 1 < CH) {
; #pragma unroll
;                     for (int u = 0; u < KT / 4; ++u)
; #pragma unroll
;                         for (int a5 = 0; a5 < 5; ++a5) nx[a5][u] = vp0[(i + 1) * 16 + a5 * CH * 16 + u];
;                     nvv = vbuf[(i + 1) * 64 + row];
;                 }
;                 f32x2 acc2 = s[0] * kk2[0];
; #pragma unroll
;                 for (int j = 1; j < KT / 2; ++j) acc2 = __builtin_elementwise_fma(s[j], kk2[j], acc2);
;                 float sa = acc2[0] + acc2[1];
;                 sa += dppf<0xB1>(sa); sa += dppf<0x4E>(sa); sa += dppf<0x141>(sa);
;                 if (TPR == 16) sa += dppf<0x140>(sa);
;                 sa = -sa;
;                 const f32x2 sa2 = (f32x2){sa, sa}, vv2 = (f32x2){vv, vv};
;                 f32x2 y2 = (f32x2){0.f, 0.f};
; #pragma unroll
;                 for (int j = 0; j < KT / 2; ++j) {
;                     s[j] = __builtin_elementwise_fma(s[j], w2[j], __builtin_elementwise_fma(sa2, b2[j], vv2 * kd2[j]));
;                     y2 = __builtin_elementwise_fma(s[j], r2[j], y2);
;                 }
;                 float y = y2[0] + y2[1];
;                 y += dppf<0xB1>(y); y += dppf<0x4E>(y);
;                 yv[i] = y;
;             }
;             if ((q & 3) == 0) {
; #pragma unroll
	v_add_f32_dpp v124, v124, v124 quad_perm:[1,0,3,2] row_mask:0xf bank_mask:0xf bound_ctrl:1
	v_add_f32_dpp v125, v125, v125 quad_perm:[1,0,3,2] row_mask:0xf bank_mask:0xf bound_ctrl:1
	ds_read_b128 v[24:27], v200 offset:768
	v_add_f32_dpp v124, v124, v124 quad_perm:[2,3,0,1] row_mask:0xf bank_mask:0xf bound_ctrl:1
	v_add_f32_dpp v125, v125, v125 quad_perm:[2,3,0,1] row_mask:0xf bank_mask:0xf bound_ctrl:1
	ds_write2st64_b32 v202, v124, v125 offset0:98 offset1:99
	ds_read_b128 v[48:51], v200 offset:13056
	ds_read_b128 v[32:35], v200 offset:8960
	ds_read_b128 v[28:31], v200 offset:4864
	ds_read_b128 v[100:103], v200 offset:17152
	v_pk_mul_f32 v[104:105], v[0:1], v[4:5]
	v_pk_mul_f32 v[106:107], v[204:205], v[4:5]
	v_pk_fma_f32 v[104:105], v[2:3], v[6:7], v[104:105]
	v_pk_fma_f32 v[106:107], v[206:207], v[6:7], v[106:107]
	v_add_f32_e32 v108, v104, v105
	v_add_f32_e32 v110, v106, v107
	v_pk_mul_f32 v[112:113], v[16:17], v[188:189] op_sel_hi:[1,0]
	v_add_f32_dpp v108, v108, v108 quad_perm:[1,0,3,2] row_mask:0xf bank_mask:0xf bound_ctrl:1
	v_add_f32_dpp v110, v110, v110 quad_perm:[1,0,3,2] row_mask:0xf bank_mask:0xf bound_ctrl:1
	v_pk_mul_f32 v[116:117], v[16:17], v[192:193] op_sel_hi:[1,0]
	v_add_f32_dpp v108, v108, v108 quad_perm:[2,3,0,1] row_mask:0xf bank_mask:0xf bound_ctrl:1
	v_add_f32_dpp v110, v110, v110 quad_perm:[2,3,0,1] row_mask:0xf bank_mask:0xf bound_ctrl:1
	v_pk_mul_f32 v[114:115], v[18:19], v[188:189] op_sel_hi:[1,0]
	v_add_f32_dpp v108, v108, v108 row_half_mirror row_mask:0xf bank_mask:0xf bound_ctrl:1
	v_add_f32_dpp v110, v110, v110 row_half_mirror row_mask:0xf bank_mask:0xf bound_ctrl:1
	v_pk_mul_f32 v[118:119], v[18:19], v[192:193] op_sel_hi:[1,0]
	v_add_f32_dpp v108, v108, v108 row_mirror row_mask:0xf bank_mask:0xf bound_ctrl:1
	v_add_f32_dpp v110, v110, v110 row_mirror row_mask:0xf bank_mask:0xf bound_ctrl:1
	v_pk_fma_f32 v[112:113], v[108:109], v[12:13], v[112:113] op_sel_hi:[0,1,1] neg_lo:[1,0,0] neg_hi:[1,0,0]
	v_pk_fma_f32 v[116:117], v[110:111], v[12:13], v[116:117] op_sel_hi:[0,1,1] neg_lo:[1,0,0] neg_hi:[1,0,0]
	v_pk_fma_f32 v[114:115], v[108:109], v[14:15], v[114:115] op_sel_hi:[0,1,1] neg_lo:[1,0,0] neg_hi:[1,0,0]
	v_pk_fma_f32 v[118:119], v[110:111], v[14:15], v[118:119] op_sel_hi:[0,1,1] neg_lo:[1,0,0] neg_hi:[1,0,0]
	v_pk_fma_f32 v[0:1], v[0:1], v[8:9], v[112:113]
	v_pk_fma_f32 v[204:205], v[204:205], v[8:9], v[116:117]
	v_pk_fma_f32 v[2:3], v[2:3], v[10:11], v[114:115]
	v_pk_fma_f32 v[206:207], v[206:207], v[10:11], v[118:119]
	v_pk_fma_f32 v[120:121], v[0:1], v[20:21], 0 op_sel_hi:[1,1,0]
	v_pk_fma_f32 v[122:123], v[204:205], v[20:21], 0 op_sel_hi:[1,1,0]
	v_pk_fma_f32 v[120:121], v[2:3], v[22:23], v[120:121]
	v_pk_fma_f32 v[122:123], v[206:207], v[22:23], v[122:123]
	v_add_f32_e32 v124, v120, v121
	v_add_f32_e32 v125, v122, v123
	s_waitcnt lgkmcnt(0)
	v_add_f32_dpp v124, v124, v124 quad_perm:[1,0,3,2] row_mask:0xf bank_mask:0xf bound_ctrl:1
	v_add_f32_dpp v125, v125, v125 quad_perm:[1,0,3,2] row_mask:0xf bank_mask:0xf bound_ctrl:1
	ds_read2st64_b32 v[186:187], v201 offset0:84 offset1:85
	v_add_f32_dpp v124, v124, v124 quad_perm:[2,3,0,1] row_mask:0xf bank_mask:0xf bound_ctrl:1
	v_add_f32_dpp v125, v125, v125 quad_perm:[2,3,0,1] row_mask:0xf bank_mask:0xf bound_ctrl:1
	ds_write2st64_b32 v202, v124, v125 offset0:100 offset1:101
	ds_read2st64_b32 v[190:191], v203 offset0:84 offset1:85
	ds_read_b128 v[4:7], v200 offset:1024
	ds_read_b128 v[16:19], v200 offset:13312
	ds_read_b128 v[12:15], v200 offset:9216
	ds_read_b128 v[8:11], v200 offset:5120
	ds_read_b128 v[20:23], v200 offset:17408
	v_pk_mul_f32 v[104:105], v[0:1], v[24:25]
	v_pk_mul_f32 v[106:107], v[204:205], v[24:25]
	v_pk_fma_f32 v[104:105], v[2:3], v[26:27], v[104:105]
	v_pk_fma_f32 v[106:107], v[206:207], v[26:27], v[106:107]
	v_add_f32_e32 v108, v104, v105
	v_add_f32_e32 v110, v106, v107
	v_pk_mul_f32 v[112:113], v[48:49], v[188:189] op_sel:[0,1] op_sel_hi:[1,1]
	v_add_f32_dpp v108, v108, v108 quad_perm:[1,0,3,2] row_mask:0xf bank_mask:0xf bound_ctrl:1
	v_add_f32_dpp v110, v110, v110 quad_perm:[1,0,3,2] row_mask:0xf bank_mask:0xf bound_ctrl:1
	v_pk_mul_f32 v[116:117], v[48:49], v[192:193] op_sel:[0,1] op_sel_hi:[1,1]
	v_add_f32_dpp v108, v108, v108 quad_perm:[2,3,0,1] row_mask:0xf bank_mask:0xf bound_ctrl:1
	v_add_f32_dpp v110, v110, v110 quad_perm:[2,3,0,1] row_mask:0xf bank_mask:0xf bound_ctrl:1
	v_pk_mul_f32 v[114:115], v[50:51], v[188:189] op_sel:[0,1] op_sel_hi:[1,1]
	v_add_f32_dpp v108, v108, v108 row_half_mirror row_mask:0xf bank_mask:0xf bound_ctrl:1
	v_add_f32_dpp v110, v110, v110 row_half_mirror row_mask:0xf bank_mask:0xf bound_ctrl:1
	v_pk_mul_f32 v[118:119], v[50:51], v[192:193] op_sel:[0,1] op_sel_hi:[1,1]
	v_add_f32_dpp v108, v108, v108 row_mirror row_mask:0xf bank_mask:0xf bound_ctrl:1
	v_add_f32_dpp v110, v110, v110 row_mirror row_mask:0xf bank_mask:0xf bound_ctrl:1
	v_pk_fma_f32 v[112:113], v[108:109], v[32:33], v[112:113] op_sel_hi:[0,1,1] neg_lo:[1,0,0] neg_hi:[1,0,0]
	v_pk_fma_f32 v[116:117], v[110:111], v[32:33], v[116:117] op_sel_hi:[0,1,1] neg_lo:[1,0,0] neg_hi:[1,0,0]
	v_pk_fma_f32 v[114:115], v[108:109], v[34:35], v[114:115] op_sel_hi:[0,1,1] neg_lo:[1,0,0] neg_hi:[1,0,0]
	v_pk_fma_f32 v[118:119], v[110:111], v[34:35], v[118:119] op_sel_hi:[0,1,1] neg_lo:[1,0,0] neg_hi:[1,0,0]
	v_pk_fma_f32 v[0:1], v[0:1], v[28:29], v[112:113]
	v_pk_fma_f32 v[204:205], v[204:205], v[28:29], v[116:117]
	v_pk_fma_f32 v[2:3], v[2:3], v[30:31], v[114:115]
	v_pk_fma_f32 v[206:207], v[206:207], v[30:31], v[118:119]
	v_pk_fma_f32 v[120:121], v[0:1], v[100:101], 0 op_sel_hi:[1,1,0]
	v_pk_fma_f32 v[122:123], v[204:205], v[100:101], 0 op_sel_hi:[1,1,0]
	v_pk_fma_f32 v[120:121], v[2:3], v[102:103], v[120:121]
	v_pk_fma_f32 v[122:123], v[206:207], v[102:103], v[122:123]
	v_add_f32_e32 v124, v120, v121
	v_add_f32_e32 v125, v122, v123
	s_waitcnt lgkmcnt(0)
; template <int KT>
; __device__ __forceinline__ void scan_block(const Ctx& C, const PV& P, int layer, int sq, int h, int d, int row0, unsigned char* smem) {
;     ...
;             for (int i = 0; i < CH; ++i) {
;                 f32x2 kk2[KT / 2], w2[KT / 2], b2[KT / 2], kd2[KT / 2], r2[KT / 2];
; #pragma unroll
;                 for (int u = 0; u < KT / 4; ++u) {
;                     kk2[2 * u] = (f32x2){nx[0][u][0], nx[0][u][1]}; kk2[2 * u + 1] = (f32x2){nx[0][u][2], nx[0][u][3]};
;                     w2[2 * u] = (f32x2){nx[1][u][0], nx[1][u][1]}; w2[2 * u + 1] = (f32x2){nx[1][u][2], nx[1][u][3]};
;                     b2[2 * u] = (f32x2){nx[2][u][0], nx[2][u][1]}; b2[2 * u + 1] = (f32x2){nx[2][u][2], nx[2][u][3]};
;                     kd2[2 * u] = (f32x2){nx[3][u][0], nx[3][u][1]}; kd2[2 * u + 1] = (f32x2){nx[3][u][2], nx[3][u][3]};
;                     r2[2 * u] = (f32x2){nx[4][u][0], nx[4][u][1]}; r2[2 * u + 1] = (f32x2){nx[4][u][2], nx[4][u][3]};
;                 }
;                 const float vv = nvv;
;                 if (i + 1 < CH) {
; #pragma unroll
;                     for (int u = 0; u < KT / 4; ++u)
; #pragma unroll
;                         for (int a5 = 0; a5 < 5; ++a5) nx[a5][u] = vp0[(i + 1) * 16 + a5 * CH * 16 + u];
;                     nvv = vbuf[(i + 1) * 64 + row];
;                 }
;                 f32x2 acc2 = s[0] * kk2[0];
; #pragma unroll
;                 for (int j = 1; j < KT / 2; ++j) acc2 = __builtin_elementwise_fma(s[j], kk2[j], acc2);
;                 float sa = acc2[0] + acc2[1];
;                 sa += dppf<0xB1>(sa); sa += dppf<0x4E>(sa); sa += dppf<0x141>(sa);
;                 if (TPR == 16) sa += dppf<0x140>(sa);
;                 sa = -sa;
;                 const f32x2 sa2 = (f32x2){sa, sa}, vv2 = (f32x2){vv, vv};
;                 f32x2 y2 = (f32x2){0.f, 0.f};
; #pragma unroll
;                 for (int j = 0; j < KT / 2; ++j) {
;                     s[j] = __builtin_elementwise_fma(s[j], w2[j], __builtin_elementwise_fma(sa2, b2[j], vv2 * kd2[j]));
;                     y2 = __builtin_elementwise_fma(s[j], r2[j], y2);
;                 }
;                 float y = y2[0] + y2[1];
;                 y += dppf<0xB1>(y); y += dppf<0x4E>(y);
;                 yv[i] = y;
;             }
;             if ((q & 3) == 0) {
; #pragma unroll
	v_add_f32_dpp v124, v124, v124 quad_perm:[1,0,3,2] row_mask:0xf bank_mask:0xf bound_ctrl:1
	v_add_f32_dpp v125, v125, v125 quad_perm:[1,0,3,2] row_mask:0xf bank_mask:0xf bound_ctrl:1
	ds_read_b128 v[24:27], v200 offset:1280
	v_add_f32_dpp v124, v124, v124 quad_perm:[2,3,0,1] row_mask:0xf bank_mask:0xf bound_ctrl:1
	v_add_f32_dpp v125, v125, v125 quad_perm:[2,3,0,1] row_mask:0xf bank_mask:0xf bound_ctrl:1
	ds_write2st64_b32 v202, v124, v125 offset0:102 offset1:103
	ds_read_b128 v[48:51], v200 offset:13568
	ds_read_b128 v[32:35], v200 offset:9472
	ds_read_b128 v[28:31], v200 offset:5376
	ds_read_b128 v[100:103], v200 offset:17664
	v_pk_mul_f32 v[104:105], v[0:1], v[4:5]
	v_pk_mul_f32 v[106:107], v[204:205], v[4:5]
	v_pk_fma_f32 v[104:105], v[2:3], v[6:7], v[104:105]
	v_pk_fma_f32 v[106:107], v[206:207], v[6:7], v[106:107]
	v_add_f32_e32 v108, v104, v105
	v_add_f32_e32 v110, v106, v107
	v_pk_mul_f32 v[112:113], v[16:17], v[186:187] op_sel_hi:[1,0]
	v_add_f32_dpp v108, v108, v108 quad_perm:[1,0,3,2] row_mask:0xf bank_mask:0xf bound_ctrl:1
	v_add_f32_dpp v110, v110, v110 quad_perm:[1,0,3,2] row_mask:0xf bank_mask:0xf bound_ctrl:1
	v_pk_mul_f32 v[116:117], v[16:17], v[190:191] op_sel_hi:[1,0]
	v_add_f32_dpp v108, v108, v108 quad_perm:[2,3,0,1] row_mask:0xf bank_mask:0xf bound_ctrl:1
	v_add_f32_dpp v110, v110, v110 quad_perm:[2,3,0,1] row_mask:0xf bank_mask:0xf bound_ctrl:1
	v_pk_mul_f32 v[114:115], v[18:19], v[186:187] op_sel_hi:[1,0]
	v_add_f32_dpp v108, v108, v108 row_half_mirror row_mask:0xf bank_mask:0xf bound_ctrl:1
	v_add_f32_dpp v110, v110, v110 row_half_mirror row_mask:0xf bank_mask:0xf bound_ctrl:1
	v_pk_mul_f32 v[118:119], v[18:19], v[190:191] op_sel_hi:[1,0]
	v_add_f32_dpp v108, v108, v108 row_mirror row_mask:0xf bank_mask:0xf bound_ctrl:1
	v_add_f32_dpp v110, v110, v110 row_mirror row_mask:0xf bank_mask:0xf bound_ctrl:1
	v_pk_fma_f32 v[112:113], v[108:109], v[12:13], v[112:113] op_sel_hi:[0,1,1] neg_lo:[1,0,0] neg_hi:[1,0,0]
	v_pk_fma_f32 v[116:117], v[110:111], v[12:13], v[116:117] op_sel_hi:[0,1,1] neg_lo:[1,0,0] neg_hi:[1,0,0]
	v_pk_fma_f32 v[114:115], v[108:109], v[14:15], v[114:115] op_sel_hi:[0,1,1] neg_lo:[1,0,0] neg_hi:[1,0,0]
	v_pk_fma_f32 v[118:119], v[110:111], v[14:15], v[118:119] op_sel_hi:[0,1,1] neg_lo:[1,0,0] neg_hi:[1,0,0]
	v_pk_fma_f32 v[0:1], v[0:1], v[8:9], v[112:113]
	v_pk_fma_f32 v[204:205], v[204:205], v[8:9], v[116:117]
	v_pk_fma_f32 v[2:3], v[2:3], v[10:11], v[114:115]
	v_pk_fma_f32 v[206:207], v[206:207], v[10:11], v[118:119]
	v_pk_fma_f32 v[120:121], v[0:1], v[20:21], 0 op_sel_hi:[1,1,0]
	v_pk_fma_f32 v[122:123], v[204:205], v[20:21], 0 op_sel_hi:[1,1,0]
	v_pk_fma_f32 v[120:121], v[2:3], v[22:23], v[120:121]
	v_pk_fma_f32 v[122:123], v[206:207], v[22:23], v[122:123]
	v_add_f32_e32 v124, v120, v121
	v_add_f32_e32 v125, v122, v123
	s_waitcnt lgkmcnt(0)
	v_add_f32_dpp v124, v124, v124 quad_perm:[1,0,3,2] row_mask:0xf bank_mask:0xf bound_ctrl:1
	v_add_f32_dpp v125, v125, v125 quad_perm:[1,0,3,2] row_mask:0xf bank_mask:0xf bound_ctrl:1
	ds_read2st64_b32 v[188:189], v201 offset0:86 offset1:87
	v_add_f32_dpp v124, v124, v124 quad_perm:[2,3,0,1] row_mask:0xf bank_mask:0xf bound_ctrl:1
	v_add_f32_dpp v125, v125, v125 quad_perm:[2,3,0,1] row_mask:0xf bank_mask:0xf bound_ctrl:1
	ds_write2st64_b32 v202, v124, v125 offset0:104 offset1:105
	ds_read2st64_b32 v[192:193], v203 offset0:86 offset1:87
	ds_read_b128 v[4:7], v200 offset:1536
	ds_read_b128 v[16:19], v200 offset:13824
	ds_read_b128 v[12:15], v200 offset:9728
	ds_read_b128 v[8:11], v200 offset:5632
	ds_read_b128 v[20:23], v200 offset:17920
	v_pk_mul_f32 v[104:105], v[0:1], v[24:25]
	v_pk_mul_f32 v[106:107], v[204:205], v[24:25]
	v_pk_fma_f32 v[104:105], v[2:3], v[26:27], v[104:105]
	v_pk_fma_f32 v[106:107], v[206:207], v[26:27], v[106:107]
	v_add_f32_e32 v108, v104, v105
	v_add_f32_e32 v110, v106, v107
	v_pk_mul_f32 v[112:113], v[48:49], v[186:187] op_sel:[0,1] op_sel_hi:[1,1]
	v_add_f32_dpp v108, v108, v108 quad_perm:[1,0,3,2] row_mask:0xf bank_mask:0xf bound_ctrl:1
	v_add_f32_dpp v110, v110, v110 quad_perm:[1,0,3,2] row_mask:0xf bank_mask:0xf bound_ctrl:1
	v_pk_mul_f32 v[116:117], v[48:49], v[190:191] op_sel:[0,1] op_sel_hi:[1,1]
	v_add_f32_dpp v108, v108, v108 quad_perm:[2,3,0,1] row_mask:0xf bank_mask:0xf bound_ctrl:1
	v_add_f32_dpp v110, v110, v110 quad_perm:[2,3,0,1] row_mask:0xf bank_mask:0xf bound_ctrl:1
	v_pk_mul_f32 v[114:115], v[50:51], v[186:187] op_sel:[0,1] op_sel_hi:[1,1]
	v_add_f32_dpp v108, v108, v108 row_half_mirror row_mask:0xf bank_mask:0xf bound_ctrl:1
	v_add_f32_dpp v110, v110, v110 row_half_mirror row_mask:0xf bank_mask:0xf bound_ctrl:1
	v_pk_mul_f32 v[118:119], v[50:51], v[190:191] op_sel:[0,1] op_sel_hi:[1,1]
	v_add_f32_dpp v108, v108, v108 row_mirror row_mask:0xf bank_mask:0xf bound_ctrl:1
	v_add_f32_dpp v110, v110, v110 row_mirror row_mask:0xf bank_mask:0xf bound_ctrl:1
	v_pk_fma_f32 v[112:113], v[108:109], v[32:33], v[112:113] op_sel_hi:[0,1,1] neg_lo:[1,0,0] neg_hi:[1,0,0]
	v_pk_fma_f32 v[116:117], v[110:111], v[32:33], v[116:117] op_sel_hi:[0,1,1] neg_lo:[1,0,0] neg_hi:[1,0,0]
	v_pk_fma_f32 v[114:115], v[108:109], v[34:35], v[114:115] op_sel_hi:[0,1,1] neg_lo:[1,0,0] neg_hi:[1,0,0]
	v_pk_fma_f32 v[118:119], v[110:111], v[34:35], v[118:119] op_sel_hi:[0,1,1] neg_lo:[1,0,0] neg_hi:[1,0,0]
	v_pk_fma_f32 v[0:1], v[0:1], v[28:29], v[112:113]
	v_pk_fma_f32 v[204:205], v[204:205], v[28:29], v[116:117]
	v_pk_fma_f32 v[2:3], v[2:3], v[30:31], v[114:115]
	v_pk_fma_f32 v[206:207], v[206:207], v[30:31], v[118:119]
	v_pk_fma_f32 v[120:121], v[0:1], v[100:101], 0 op_sel_hi:[1,1,0]
	v_pk_fma_f32 v[122:123], v[204:205], v[100:101], 0 op_sel_hi:[1,1,0]
	v_pk_fma_f32 v[120:121], v[2:3], v[102:103], v[120:121]
	v_pk_fma_f32 v[122:123], v[206:207], v[102:103], v[122:123]
	v_add_f32_e32 v124, v120, v121
	v_add_f32_e32 v125, v122, v123
	s_waitcnt lgkmcnt(0)
; template <int KT>
; __device__ __forceinline__ void scan_block(const Ctx& C, const PV& P, int layer, int sq, int h, int d, int row0, unsigned char* smem) {
;     ...
;             for (int i = 0; i < CH; ++i) {
;                 f32x2 kk2[KT / 2], w2[KT / 2], b2[KT / 2], kd2[KT / 2], r2[KT / 2];
; #pragma unroll
;                 for (int u = 0; u < KT / 4; ++u) {
;                     kk2[2 * u] = (f32x2){nx[0][u][0], nx[0][u][1]}; kk2[2 * u + 1] = (f32x2){nx[0][u][2], nx[0][u][3]};
;                     w2[2 * u] = (f32x2){nx[1][u][0], nx[1][u][1]}; w2[2 * u + 1] = (f32x2){nx[1][u][2], nx[1][u][3]};
;                     b2[2 * u] = (f32x2){nx[2][u][0], nx[2][u][1]}; b2[2 * u + 1] = (f32x2){nx[2][u][2], nx[2][u][3]};
;                     kd2[2 * u] = (f32x2){nx[3][u][0], nx[3][u][1]}; kd2[2 * u + 1] = (f32x2){nx[3][u][2], nx[3][u][3]};
;                     r2[2 * u] = (f32x2){nx[4][u][0], nx[4][u][1]}; r2[2 * u + 1] = (f32x2){nx[4][u][2], nx[4][u][3]};
;                 }
;                 const float vv = nvv;
;                 if (i + 1 < CH) {
; #pragma unroll
;                     for (int u = 0; u < KT / 4; ++u)
; #pragma unroll
;                         for (int a5 = 0; a5 < 5; ++a5) nx[a5][u] = vp0[(i + 1) * 16 + a5 * CH * 16 + u];
;                     nvv = vbuf[(i + 1) * 64 + row];
;                 }
;                 f32x2 acc2 = s[0] * kk2[0];
; #pragma unroll
;                 for (int j = 1; j < KT / 2; ++j) acc2 = __builtin_elementwise_fma(s[j], kk2[j], acc2);
;                 float sa = acc2[0] + acc2[1];
;                 sa += dppf<0xB1>(sa); sa += dppf<0x4E>(sa); sa += dppf<0x141>(sa);
;                 if (TPR == 16) sa += dppf<0x140>(sa);
;                 sa = -sa;
;                 const f32x2 sa2 = (f32x2){sa, sa}, vv2 = (f32x2){vv, vv};
;                 f32x2 y2 = (f32x2){0.f, 0.f};
; #pragma unroll
;                 for (int j = 0; j < KT / 2; ++j) {
;                     s[j] = __builtin_elementwise_fma(s[j], w2[j], __builtin_elementwise_fma(sa2, b2[j], vv2 * kd2[j]));
;                     y2 = __builtin_elementwise_fma(s[j], r2[j], y2);
;                 }
;                 float y = y2[0] + y2[1];
;                 y += dppf<0xB1>(y); y += dppf<0x4E>(y);
;                 yv[i] = y;
;             }
;             if ((q & 3) == 0) {
; #pragma unroll
	v_add_f32_dpp v124, v124, v124 quad_perm:[1,0,3,2] row_mask:0xf bank_mask:0xf bound_ctrl:1
	v_add_f32_dpp v125, v125, v125 quad_perm:[1,0,3,2] row_mask:0xf bank_mask:0xf bound_ctrl:1
	ds_read_b128 v[24:27], v200 offset:1792
	v_add_f32_dpp v124, v124, v124 quad_perm:[2,3,0,1] row_mask:0xf bank_mask:0xf bound_ctrl:1
	v_add_f32_dpp v125, v125, v125 quad_perm:[2,3,0,1] row_mask:0xf bank_mask:0xf bound_ctrl:1
	ds_write2st64_b32 v202, v124, v125 offset0:106 offset1:107
	ds_read_b128 v[48:51], v200 offset:14080
	ds_read_b128 v[32:35], v200 offset:9984
	ds_read_b128 v[28:31], v200 offset:5888
	ds_read_b128 v[100:103], v200 offset:18176
	v_pk_mul_f32 v[104:105], v[0:1], v[4:5]
	v_pk_mul_f32 v[106:107], v[204:205], v[4:5]
	v_pk_fma_f32 v[104:105], v[2:3], v[6:7], v[104:105]
	v_pk_fma_f32 v[106:107], v[206:207], v[6:7], v[106:107]
	v_add_f32_e32 v108, v104, v105
	v_add_f32_e32 v110, v106, v107
	v_pk_mul_f32 v[112:113], v[16:17], v[188:189] op_sel_hi:[1,0]
	v_add_f32_dpp v108, v108, v108 quad_perm:[1,0,3,2] row_mask:0xf bank_mask:0xf bound_ctrl:1
	v_add_f32_dpp v110, v110, v110 quad_perm:[1,0,3,2] row_mask:0xf bank_mask:0xf bound_ctrl:1
	v_pk_mul_f32 v[116:117], v[16:17], v[192:193] op_sel_hi:[1,0]
	v_add_f32_dpp v108, v108, v108 quad_perm:[2,3,0,1] row_mask:0xf bank_mask:0xf bound_ctrl:1
	v_add_f32_dpp v110, v110, v110 quad_perm:[2,3,0,1] row_mask:0xf bank_mask:0xf bound_ctrl:1
	v_pk_mul_f32 v[114:115], v[18:19], v[188:189] op_sel_hi:[1,0]
	v_add_f32_dpp v108, v108, v108 row_half_mirror row_mask:0xf bank_mask:0xf bound_ctrl:1
	v_add_f32_dpp v110, v110, v110 row_half_mirror row_mask:0xf bank_mask:0xf bound_ctrl:1
	v_pk_mul_f32 v[118:119], v[18:19], v[192:193] op_sel_hi:[1,0]
	v_add_f32_dpp v108, v108, v108 row_mirror row_mask:0xf bank_mask:0xf bound_ctrl:1
	v_add_f32_dpp v110, v110, v110 row_mirror row_mask:0xf bank_mask:0xf bound_ctrl:1
	v_pk_fma_f32 v[112:113], v[108:109], v[12:13], v[112:113] op_sel_hi:[0,1,1] neg_lo:[1,0,0] neg_hi:[1,0,0]
	v_pk_fma_f32 v[116:117], v[110:111], v[12:13], v[116:117] op_sel_hi:[0,1,1] neg_lo:[1,0,0] neg_hi:[1,0,0]
	v_pk_fma_f32 v[114:115], v[108:109], v[14:15], v[114:115] op_sel_hi:[0,1,1] neg_lo:[1,0,0] neg_hi:[1,0,0]
	v_pk_fma_f32 v[118:119], v[110:111], v[14:15], v[118:119] op_sel_hi:[0,1,1] neg_lo:[1,0,0] neg_hi:[1,0,0]
	v_pk_fma_f32 v[0:1], v[0:1], v[8:9], v[112:113]
	v_pk_fma_f32 v[204:205], v[204:205], v[8:9], v[116:117]
	v_pk_fma_f32 v[2:3], v[2:3], v[10:11], v[114:115]
	v_pk_fma_f32 v[206:207], v[206:207], v[10:11], v[118:119]
	v_pk_fma_f32 v[120:121], v[0:1], v[20:21], 0 op_sel_hi:[1,1,0]
	v_pk_fma_f32 v[122:123], v[204:205], v[20:21], 0 op_sel_hi:[1,1,0]
	v_pk_fma_f32 v[120:121], v[2:3], v[22:23], v[120:121]
	v_pk_fma_f32 v[122:123], v[206:207], v[22:23], v[122:123]
	v_add_f32_e32 v124, v120, v121
	v_add_f32_e32 v125, v122, v123
	s_waitcnt lgkmcnt(0)
	v_add_f32_dpp v124, v124, v124 quad_perm:[1,0,3,2] row_mask:0xf bank_mask:0xf bound_ctrl:1
	v_add_f32_dpp v125, v125, v125 quad_perm:[1,0,3,2] row_mask:0xf bank_mask:0xf bound_ctrl:1
	ds_read2st64_b32 v[186:187], v201 offset0:88 offset1:89
	v_add_f32_dpp v124, v124, v124 quad_perm:[2,3,0,1] row_mask:0xf bank_mask:0xf bound_ctrl:1
	v_add_f32_dpp v125, v125, v125 quad_perm:[2,3,0,1] row_mask:0xf bank_mask:0xf bound_ctrl:1
	ds_write2st64_b32 v202, v124, v125 offset0:108 offset1:109
	ds_read2st64_b32 v[190:191], v203 offset0:88 offset1:89
	ds_read_b128 v[4:7], v200 offset:2048
	ds_read_b128 v[16:19], v200 offset:14336
	ds_read_b128 v[12:15], v200 offset:10240
	ds_read_b128 v[8:11], v200 offset:6144
	ds_read_b128 v[20:23], v200 offset:18432
	v_pk_mul_f32 v[104:105], v[0:1], v[24:25]
	v_pk_mul_f32 v[106:107], v[204:205], v[24:25]
	v_pk_fma_f32 v[104:105], v[2:3], v[26:27], v[104:105]
	v_pk_fma_f32 v[106:107], v[206:207], v[26:27], v[106:107]
	v_add_f32_e32 v108, v104, v105
	v_add_f32_e32 v110, v106, v107
	v_pk_mul_f32 v[112:113], v[48:49], v[188:189] op_sel:[0,1] op_sel_hi:[1,1]
	v_add_f32_dpp v108, v108, v108 quad_perm:[1,0,3,2] row_mask:0xf bank_mask:0xf bound_ctrl:1
	v_add_f32_dpp v110, v110, v110 quad_perm:[1,0,3,2] row_mask:0xf bank_mask:0xf bound_ctrl:1
	v_pk_mul_f32 v[116:117], v[48:49], v[192:193] op_sel:[0,1] op_sel_hi:[1,1]
	v_add_f32_dpp v108, v108, v108 quad_perm:[2,3,0,1] row_mask:0xf bank_mask:0xf bound_ctrl:1
	v_add_f32_dpp v110, v110, v110 quad_perm:[2,3,0,1] row_mask:0xf bank_mask:0xf bound_ctrl:1
	v_pk_mul_f32 v[114:115], v[50:51], v[188:189] op_sel:[0,1] op_sel_hi:[1,1]
	v_add_f32_dpp v108, v108, v108 row_half_mirror row_mask:0xf bank_mask:0xf bound_ctrl:1
	v_add_f32_dpp v110, v110, v110 row_half_mirror row_mask:0xf bank_mask:0xf bound_ctrl:1
	v_pk_mul_f32 v[118:119], v[50:51], v[192:193] op_sel:[0,1] op_sel_hi:[1,1]
	v_add_f32_dpp v108, v108, v108 row_mirror row_mask:0xf bank_mask:0xf bound_ctrl:1
	v_add_f32_dpp v110, v110, v110 row_mirror row_mask:0xf bank_mask:0xf bound_ctrl:1
	v_pk_fma_f32 v[112:113], v[108:109], v[32:33], v[112:113] op_sel_hi:[0,1,1] neg_lo:[1,0,0] neg_hi:[1,0,0]
	v_pk_fma_f32 v[116:117], v[110:111], v[32:33], v[116:117] op_sel_hi:[0,1,1] neg_lo:[1,0,0] neg_hi:[1,0,0]
	v_pk_fma_f32 v[114:115], v[108:109], v[34:35], v[114:115] op_sel_hi:[0,1,1] neg_lo:[1,0,0] neg_hi:[1,0,0]
	v_pk_fma_f32 v[118:119], v[110:111], v[34:35], v[118:119] op_sel_hi:[0,1,1] neg_lo:[1,0,0] neg_hi:[1,0,0]
	v_pk_fma_f32 v[0:1], v[0:1], v[28:29], v[112:113]
	v_pk_fma_f32 v[204:205], v[204:205], v[28:29], v[116:117]
	v_pk_fma_f32 v[2:3], v[2:3], v[30:31], v[114:115]
	v_pk_fma_f32 v[206:207], v[206:207], v[30:31], v[118:119]
	v_pk_fma_f32 v[120:121], v[0:1], v[100:101], 0 op_sel_hi:[1,1,0]
	v_pk_fma_f32 v[122:123], v[204:205], v[100:101], 0 op_sel_hi:[1,1,0]
	v_pk_fma_f32 v[120:121], v[2:3], v[102:103], v[120:121]
	v_pk_fma_f32 v[122:123], v[206:207], v[102:103], v[122:123]
	v_add_f32_e32 v124, v120, v121
	v_add_f32_e32 v125, v122, v123
	s_waitcnt lgkmcnt(0)
; template <int KT>
; __device__ __forceinline__ void scan_block(const Ctx& C, const PV& P, int layer, int sq, int h, int d, int row0, unsigned char* smem) {
;     ...
;             for (int i = 0; i < CH; ++i) {
;                 f32x2 kk2[KT / 2], w2[KT / 2], b2[KT / 2], kd2[KT / 2], r2[KT / 2];
; #pragma unroll
;                 for (int u = 0; u < KT / 4; ++u) {
;                     kk2[2 * u] = (f32x2){nx[0][u][0], nx[0][u][1]}; kk2[2 * u + 1] = (f32x2){nx[0][u][2], nx[0][u][3]};
;                     w2[2 * u] = (f32x2){nx[1][u][0], nx[1][u][1]}; w2[2 * u + 1] = (f32x2){nx[1][u][2], nx[1][u][3]};
;                     b2[2 * u] = (f32x2){nx[2][u][0], nx[2][u][1]}; b2[2 * u + 1] = (f32x2){nx[2][u][2], nx[2][u][3]};
;                     kd2[2 * u] = (f32x2){nx[3][u][0], nx[3][u][1]}; kd2[2 * u + 1] = (f32x2){nx[3][u][2], nx[3][u][3]};
;                     r2[2 * u] = (f32x2){nx[4][u][0], nx[4][u][1]}; r2[2 * u + 1] = (f32x2){nx[4][u][2], nx[4][u][3]};
;                 }
;                 const float vv = nvv;
;                 if (i + 1 < CH) {
; #pragma unroll
;                     for (int u = 0; u < KT / 4; ++u)
; #pragma unroll
;                         for (int a5 = 0; a5 < 5; ++a5) nx[a5][u] = vp0[(i + 1) * 16 + a5 * CH * 16 + u];
;                     nvv = vbuf[(i + 1) * 64 + row];
;                 }
;                 f32x2 acc2 = s[0] * kk2[0];
; #pragma unroll
;                 for (int j = 1; j < KT / 2; ++j) acc2 = __builtin_elementwise_fma(s[j], kk2[j], acc2);
;                 float sa = acc2[0] + acc2[1];
;                 sa += dppf<0xB1>(sa); sa += dppf<0x4E>(sa); sa += dppf<0x141>(sa);
;                 if (TPR == 16) sa += dppf<0x140>(sa);
;                 sa = -sa;
;                 const f32x2 sa2 = (f32x2){sa, sa}, vv2 = (f32x2){vv, vv};
;                 f32x2 y2 = (f32x2){0.f, 0.f};
; #pragma unroll
;                 for (int j = 0; j < KT / 2; ++j) {
;                     s[j] = __builtin_elementwise_fma(s[j], w2[j], __builtin_elementwise_fma(sa2, b2[j], vv2 * kd2[j]));
;                     y2 = __builtin_elementwise_fma(s[j], r2[j], y2);
;                 }
;                 float y = y2[0] + y2[1];
;                 y += dppf<0xB1>(y); y += dppf<0x4E>(y);
;                 yv[i] = y;
;             }
;             if ((q & 3) == 0) {
; #pragma unroll
	v_add_f32_dpp v124, v124, v124 quad_perm:[1,0,3,2] row_mask:0xf bank_mask:0xf bound_ctrl:1
	v_add_f32_dpp v125, v125, v125 quad_perm:[1,0,3,2] row_mask:0xf bank_mask:0xf bound_ctrl:1
	ds_read_b128 v[24:27], v200 offset:2304
	v_add_f32_dpp v124, v124, v124 quad_perm:[2,3,0,1] row_mask:0xf bank_mask:0xf bound_ctrl:1
	v_add_f32_dpp v125, v125, v125 quad_perm:[2,3,0,1] row_mask:0xf bank_mask:0xf bound_ctrl:1
	ds_write2st64_b32 v202, v124, v125 offset0:110 offset1:111
	ds_read_b128 v[48:51], v200 offset:14592
	ds_read_b128 v[32:35], v200 offset:10496
	ds_read_b128 v[28:31], v200 offset:6400
	ds_read_b128 v[100:103], v200 offset:18688
	v_pk_mul_f32 v[104:105], v[0:1], v[4:5]
	v_pk_mul_f32 v[106:107], v[204:205], v[4:5]
	v_pk_fma_f32 v[104:105], v[2:3], v[6:7], v[104:105]
	v_pk_fma_f32 v[106:107], v[206:207], v[6:7], v[106:107]
	v_add_f32_e32 v108, v104, v105
	v_add_f32_e32 v110, v106, v107
	v_pk_mul_f32 v[112:113], v[16:17], v[186:187] op_sel_hi:[1,0]
	v_add_f32_dpp v108, v108, v108 quad_perm:[1,0,3,2] row_mask:0xf bank_mask:0xf bound_ctrl:1
	v_add_f32_dpp v110, v110, v110 quad_perm:[1,0,3,2] row_mask:0xf bank_mask:0xf bound_ctrl:1
	v_pk_mul_f32 v[116:117], v[16:17], v[190:191] op_sel_hi:[1,0]
	v_add_f32_dpp v108, v108, v108 quad_perm:[2,3,0,1] row_mask:0xf bank_mask:0xf bound_ctrl:1
	v_add_f32_dpp v110, v110, v110 quad_perm:[2,3,0,1] row_mask:0xf bank_mask:0xf bound_ctrl:1
	v_pk_mul_f32 v[114:115], v[18:19], v[186:187] op_sel_hi:[1,0]
	v_add_f32_dpp v108, v108, v108 row_half_mirror row_mask:0xf bank_mask:0xf bound_ctrl:1
	v_add_f32_dpp v110, v110, v110 row_half_mirror row_mask:0xf bank_mask:0xf bound_ctrl:1
	v_pk_mul_f32 v[118:119], v[18:19], v[190:191] op_sel_hi:[1,0]
	v_add_f32_dpp v108, v108, v108 row_mirror row_mask:0xf bank_mask:0xf bound_ctrl:1
	v_add_f32_dpp v110, v110, v110 row_mirror row_mask:0xf bank_mask:0xf bound_ctrl:1
	v_pk_fma_f32 v[112:113], v[108:109], v[12:13], v[112:113] op_sel_hi:[0,1,1] neg_lo:[1,0,0] neg_hi:[1,0,0]
	v_pk_fma_f32 v[116:117], v[110:111], v[12:13], v[116:117] op_sel_hi:[0,1,1] neg_lo:[1,0,0] neg_hi:[1,0,0]
	v_pk_fma_f32 v[114:115], v[108:109], v[14:15], v[114:115] op_sel_hi:[0,1,1] neg_lo:[1,0,0] neg_hi:[1,0,0]
	v_pk_fma_f32 v[118:119], v[110:111], v[14:15], v[118:119] op_sel_hi:[0,1,1] neg_lo:[1,0,0] neg_hi:[1,0,0]
	v_pk_fma_f32 v[0:1], v[0:1], v[8:9], v[112:113]
	v_pk_fma_f32 v[204:205], v[204:205], v[8:9], v[116:117]
	v_pk_fma_f32 v[2:3], v[2:3], v[10:11], v[114:115]
	v_pk_fma_f32 v[206:207], v[206:207], v[10:11], v[118:119]
	v_pk_fma_f32 v[120:121], v[0:1], v[20:21], 0 op_sel_hi:[1,1,0]
	v_pk_fma_f32 v[122:123], v[204:205], v[20:21], 0 op_sel_hi:[1,1,0]
	v_pk_fma_f32 v[120:121], v[2:3], v[22:23], v[120:121]
	v_pk_fma_f32 v[122:123], v[206:207], v[22:23], v[122:123]
	v_add_f32_e32 v124, v120, v121
	v_add_f32_e32 v125, v122, v123
	s_waitcnt lgkmcnt(0)
	v_add_f32_dpp v124, v124, v124 quad_perm:[1,0,3,2] row_mask:0xf bank_mask:0xf bound_ctrl:1
	v_add_f32_dpp v125, v125, v125 quad_perm:[1,0,3,2] row_mask:0xf bank_mask:0xf bound_ctrl:1
	ds_read2st64_b32 v[188:189], v201 offset0:90 offset1:91
	v_add_f32_dpp v124, v124, v124 quad_perm:[2,3,0,1] row_mask:0xf bank_mask:0xf bound_ctrl:1
	v_add_f32_dpp v125, v125, v125 quad_perm:[2,3,0,1] row_mask:0xf bank_mask:0xf bound_ctrl:1
	ds_write2st64_b32 v202, v124, v125 offset0:112 offset1:113
	ds_read2st64_b32 v[192:193], v203 offset0:90 offset1:91
	ds_read_b128 v[4:7], v200 offset:2560
	ds_read_b128 v[16:19], v200 offset:14848
	ds_read_b128 v[12:15], v200 offset:10752
	ds_read_b128 v[8:11], v200 offset:6656
	ds_read_b128 v[20:23], v200 offset:18944
	v_pk_mul_f32 v[104:105], v[0:1], v[24:25]
	v_pk_mul_f32 v[106:107], v[204:205], v[24:25]
	v_pk_fma_f32 v[104:105], v[2:3], v[26:27], v[104:105]
	v_pk_fma_f32 v[106:107], v[206:207], v[26:27], v[106:107]
	v_add_f32_e32 v108, v104, v105
	v_add_f32_e32 v110, v106, v107
	v_pk_mul_f32 v[112:113], v[48:49], v[186:187] op_sel:[0,1] op_sel_hi:[1,1]
	v_add_f32_dpp v108, v108, v108 quad_perm:[1,0,3,2] row_mask:0xf bank_mask:0xf bound_ctrl:1
	v_add_f32_dpp v110, v110, v110 quad_perm:[1,0,3,2] row_mask:0xf bank_mask:0xf bound_ctrl:1
	v_pk_mul_f32 v[116:117], v[48:49], v[190:191] op_sel:[0,1] op_sel_hi:[1,1]
	v_add_f32_dpp v108, v108, v108 quad_perm:[2,3,0,1] row_mask:0xf bank_mask:0xf bound_ctrl:1
	v_add_f32_dpp v110, v110, v110 quad_perm:[2,3,0,1] row_mask:0xf bank_mask:0xf bound_ctrl:1
	v_pk_mul_f32 v[114:115], v[50:51], v[186:187] op_sel:[0,1] op_sel_hi:[1,1]
	v_add_f32_dpp v108, v108, v108 row_half_mirror row_mask:0xf bank_mask:0xf bound_ctrl:1
	v_add_f32_dpp v110, v110, v110 row_half_mirror row_mask:0xf bank_mask:0xf bound_ctrl:1
	v_pk_mul_f32 v[118:119], v[50:51], v[190:191] op_sel:[0,1] op_sel_hi:[1,1]
	v_add_f32_dpp v108, v108, v108 row_mirror row_mask:0xf bank_mask:0xf bound_ctrl:1
	v_add_f32_dpp v110, v110, v110 row_mirror row_mask:0xf bank_mask:0xf bound_ctrl:1
	v_pk_fma_f32 v[112:113], v[108:109], v[32:33], v[112:113] op_sel_hi:[0,1,1] neg_lo:[1,0,0] neg_hi:[1,0,0]
	v_pk_fma_f32 v[116:117], v[110:111], v[32:33], v[116:117] op_sel_hi:[0,1,1] neg_lo:[1,0,0] neg_hi:[1,0,0]
	v_pk_fma_f32 v[114:115], v[108:109], v[34:35], v[114:115] op_sel_hi:[0,1,1] neg_lo:[1,0,0] neg_hi:[1,0,0]
	v_pk_fma_f32 v[118:119], v[110:111], v[34:35], v[118:119] op_sel_hi:[0,1,1] neg_lo:[1,0,0] neg_hi:[1,0,0]
	v_pk_fma_f32 v[0:1], v[0:1], v[28:29], v[112:113]
	v_pk_fma_f32 v[204:205], v[204:205], v[28:29], v[116:117]
	v_pk_fma_f32 v[2:3], v[2:3], v[30:31], v[114:115]
	v_pk_fma_f32 v[206:207], v[206:207], v[30:31], v[118:119]
	v_pk_fma_f32 v[120:121], v[0:1], v[100:101], 0 op_sel_hi:[1,1,0]
	v_pk_fma_f32 v[122:123], v[204:205], v[100:101], 0 op_sel_hi:[1,1,0]
	v_pk_fma_f32 v[120:121], v[2:3], v[102:103], v[120:121]
	v_pk_fma_f32 v[122:123], v[206:207], v[102:103], v[122:123]
	v_add_f32_e32 v124, v120, v121
	v_add_f32_e32 v125, v122, v123
	s_waitcnt lgkmcnt(0)
; template <int KT>
; __device__ __forceinline__ void scan_block(const Ctx& C, const PV& P, int layer, int sq, int h, int d, int row0, unsigned char* smem) {
;     ...
;             for (int i = 0; i < CH; ++i) {
;                 f32x2 kk2[KT / 2], w2[KT / 2], b2[KT / 2], kd2[KT / 2], r2[KT / 2];
; #pragma unroll
;                 for (int u = 0; u < KT / 4; ++u) {
;                     kk2[2 * u] = (f32x2){nx[0][u][0], nx[0][u][1]}; kk2[2 * u + 1] = (f32x2){nx[0][u][2], nx[0][u][3]};
;                     w2[2 * u] = (f32x2){nx[1][u][0], nx[1][u][1]}; w2[2 * u + 1] = (f32x2){nx[1][u][2], nx[1][u][3]};
;                     b2[2 * u] = (f32x2){nx[2][u][0], nx[2][u][1]}; b2[2 * u + 1] = (f32x2){nx[2][u][2], nx[2][u][3]};
;                     kd2[2 * u] = (f32x2){nx[3][u][0], nx[3][u][1]}; kd2[2 * u + 1] = (f32x2){nx[3][u][2], nx[3][u][3]};
;                     r2[2 * u] = (f32x2){nx[4][u][0], nx[4][u][1]}; r2[2 * u + 1] = (f32x2){nx[4][u][2], nx[4][u][3]};
;                 }
;                 const float vv = nvv;
;                 if (i + 1 < CH) {
; #pragma unroll
;                     for (int u = 0; u < KT / 4; ++u)
; #pragma unroll
;                         for (int a5 = 0; a5 < 5; ++a5) nx[a5][u] = vp0[(i + 1) * 16 + a5 * CH * 16 + u];
;                     nvv = vbuf[(i + 1) * 64 + row];
;                 }
;                 f32x2 acc2 = s[0] * kk2[0];
; #pragma unroll
;                 for (int j = 1; j < KT / 2; ++j) acc2 = __builtin_elementwise_fma(s[j], kk2[j], acc2);
;                 float sa = acc2[0] + acc2[1];
;                 sa += dppf<0xB1>(sa); sa += dppf<0x4E>(sa); sa += dppf<0x141>(sa);
;                 if (TPR == 16) sa += dppf<0x140>(sa);
;                 sa = -sa;
;                 const f32x2 sa2 = (f32x2){sa, sa}, vv2 = (f32x2){vv, vv};
;                 f32x2 y2 = (f32x2){0.f, 0.f};
; #pragma unroll
;                 for (int j = 0; j < KT / 2; ++j) {
;                     s[j] = __builtin_elementwise_fma(s[j], w2[j], __builtin_elementwise_fma(sa2, b2[j], vv2 * kd2[j]));
;                     y2 = __builtin_elementwise_fma(s[j], r2[j], y2);
;                 }
;                 float y = y2[0] + y2[1];
;                 y += dppf<0xB1>(y); y += dppf<0x4E>(y);
;                 yv[i] = y;
;             }
;             if ((q & 3) == 0) {
; #pragma unroll
	v_add_f32_dpp v124, v124, v124 quad_perm:[1,0,3,2] row_mask:0xf bank_mask:0xf bound_ctrl:1
	v_add_f32_dpp v125, v125, v125 quad_perm:[1,0,3,2] row_mask:0xf bank_mask:0xf bound_ctrl:1
	ds_read_b128 v[24:27], v200 offset:2816
	v_add_f32_dpp v124, v124, v124 quad_perm:[2,3,0,1] row_mask:0xf bank_mask:0xf bound_ctrl:1
	v_add_f32_dpp v125, v125, v125 quad_perm:[2,3,0,1] row_mask:0xf bank_mask:0xf bound_ctrl:1
	ds_write2st64_b32 v202, v124, v125 offset0:114 offset1:115
	ds_read_b128 v[48:51], v200 offset:15104
	ds_read_b128 v[32:35], v200 offset:11008
	ds_read_b128 v[28:31], v200 offset:6912
	ds_read_b128 v[100:103], v200 offset:19200
	v_pk_mul_f32 v[104:105], v[0:1], v[4:5]
	v_pk_mul_f32 v[106:107], v[204:205], v[4:5]
	v_pk_fma_f32 v[104:105], v[2:3], v[6:7], v[104:105]
	v_pk_fma_f32 v[106:107], v[206:207], v[6:7], v[106:107]
	v_add_f32_e32 v108, v104, v105
	v_add_f32_e32 v110, v106, v107
	v_pk_mul_f32 v[112:113], v[16:17], v[188:189] op_sel_hi:[1,0]
	v_add_f32_dpp v108, v108, v108 quad_perm:[1,0,3,2] row_mask:0xf bank_mask:0xf bound_ctrl:1
	v_add_f32_dpp v110, v110, v110 quad_perm:[1,0,3,2] row_mask:0xf bank_mask:0xf bound_ctrl:1
	v_pk_mul_f32 v[116:117], v[16:17], v[192:193] op_sel_hi:[1,0]
	v_add_f32_dpp v108, v108, v108 quad_perm:[2,3,0,1] row_mask:0xf bank_mask:0xf bound_ctrl:1
	v_add_f32_dpp v110, v110, v110 quad_perm:[2,3,0,1] row_mask:0xf bank_mask:0xf bound_ctrl:1
	v_pk_mul_f32 v[114:115], v[18:19], v[188:189] op_sel_hi:[1,0]
	v_add_f32_dpp v108, v108, v108 row_half_mirror row_mask:0xf bank_mask:0xf bound_ctrl:1
	v_add_f32_dpp v110, v110, v110 row_half_mirror row_mask:0xf bank_mask:0xf bound_ctrl:1
	v_pk_mul_f32 v[118:119], v[18:19], v[192:193] op_sel_hi:[1,0]
	v_add_f32_dpp v108, v108, v108 row_mirror row_mask:0xf bank_mask:0xf bound_ctrl:1
	v_add_f32_dpp v110, v110, v110 row_mirror row_mask:0xf bank_mask:0xf bound_ctrl:1
	v_pk_fma_f32 v[112:113], v[108:109], v[12:13], v[112:113] op_sel_hi:[0,1,1] neg_lo:[1,0,0] neg_hi:[1,0,0]
	v_pk_fma_f32 v[116:117], v[110:111], v[12:13], v[116:117] op_sel_hi:[0,1,1] neg_lo:[1,0,0] neg_hi:[1,0,0]
	v_pk_fma_f32 v[114:115], v[108:109], v[14:15], v[114:115] op_sel_hi:[0,1,1] neg_lo:[1,0,0] neg_hi:[1,0,0]
	v_pk_fma_f32 v[118:119], v[110:111], v[14:15], v[118:119] op_sel_hi:[0,1,1] neg_lo:[1,0,0] neg_hi:[1,0,0]
	v_pk_fma_f32 v[0:1], v[0:1], v[8:9], v[112:113]
	v_pk_fma_f32 v[204:205], v[204:205], v[8:9], v[116:117]
	v_pk_fma_f32 v[2:3], v[2:3], v[10:11], v[114:115]
	v_pk_fma_f32 v[206:207], v[206:207], v[10:11], v[118:119]
	v_pk_fma_f32 v[120:121], v[0:1], v[20:21], 0 op_sel_hi:[1,1,0]
	v_pk_fma_f32 v[122:123], v[204:205], v[20:21], 0 op_sel_hi:[1,1,0]
	v_pk_fma_f32 v[120:121], v[2:3], v[22:23], v[120:121]
	v_pk_fma_f32 v[122:123], v[206:207], v[22:23], v[122:123]
	v_add_f32_e32 v124, v120, v121
	v_add_f32_e32 v125, v122, v123
	s_waitcnt lgkmcnt(0)
	v_add_f32_dpp v124, v124, v124 quad_perm:[1,0,3,2] row_mask:0xf bank_mask:0xf bound_ctrl:1
	v_add_f32_dpp v125, v125, v125 quad_perm:[1,0,3,2] row_mask:0xf bank_mask:0xf bound_ctrl:1
	ds_read2st64_b32 v[186:187], v201 offset0:92 offset1:93
	v_add_f32_dpp v124, v124, v124 quad_perm:[2,3,0,1] row_mask:0xf bank_mask:0xf bound_ctrl:1
	v_add_f32_dpp v125, v125, v125 quad_perm:[2,3,0,1] row_mask:0xf bank_mask:0xf bound_ctrl:1
	ds_write2st64_b32 v202, v124, v125 offset0:116 offset1:117
	ds_read2st64_b32 v[190:191], v203 offset0:92 offset1:93
	ds_read_b128 v[4:7], v200 offset:3072
	ds_read_b128 v[16:19], v200 offset:15360
	ds_read_b128 v[12:15], v200 offset:11264
	ds_read_b128 v[8:11], v200 offset:7168
	ds_read_b128 v[20:23], v200 offset:19456
	v_pk_mul_f32 v[104:105], v[0:1], v[24:25]
	v_pk_mul_f32 v[106:107], v[204:205], v[24:25]
	v_pk_fma_f32 v[104:105], v[2:3], v[26:27], v[104:105]
	v_pk_fma_f32 v[106:107], v[206:207], v[26:27], v[106:107]
	v_add_f32_e32 v108, v104, v105
	v_add_f32_e32 v110, v106, v107
	v_pk_mul_f32 v[112:113], v[48:49], v[188:189] op_sel:[0,1] op_sel_hi:[1,1]
	v_add_f32_dpp v108, v108, v108 quad_perm:[1,0,3,2] row_mask:0xf bank_mask:0xf bound_ctrl:1
	v_add_f32_dpp v110, v110, v110 quad_perm:[1,0,3,2] row_mask:0xf bank_mask:0xf bound_ctrl:1
	v_pk_mul_f32 v[116:117], v[48:49], v[192:193] op_sel:[0,1] op_sel_hi:[1,1]
	v_add_f32_dpp v108, v108, v108 quad_perm:[2,3,0,1] row_mask:0xf bank_mask:0xf bound_ctrl:1
	v_add_f32_dpp v110, v110, v110 quad_perm:[2,3,0,1] row_mask:0xf bank_mask:0xf bound_ctrl:1
	v_pk_mul_f32 v[114:115], v[50:51], v[188:189] op_sel:[0,1] op_sel_hi:[1,1]
	v_add_f32_dpp v108, v108, v108 row_half_mirror row_mask:0xf bank_mask:0xf bound_ctrl:1
	v_add_f32_dpp v110, v110, v110 row_half_mirror row_mask:0xf bank_mask:0xf bound_ctrl:1
	v_pk_mul_f32 v[118:119], v[50:51], v[192:193] op_sel:[0,1] op_sel_hi:[1,1]
	v_add_f32_dpp v108, v108, v108 row_mirror row_mask:0xf bank_mask:0xf bound_ctrl:1
	v_add_f32_dpp v110, v110, v110 row_mirror row_mask:0xf bank_mask:0xf bound_ctrl:1
	v_pk_fma_f32 v[112:113], v[108:109], v[32:33], v[112:113] op_sel_hi:[0,1,1] neg_lo:[1,0,0] neg_hi:[1,0,0]
	v_pk_fma_f32 v[116:117], v[110:111], v[32:33], v[116:117] op_sel_hi:[0,1,1] neg_lo:[1,0,0] neg_hi:[1,0,0]
	v_pk_fma_f32 v[114:115], v[108:109], v[34:35], v[114:115] op_sel_hi:[0,1,1] neg_lo:[1,0,0] neg_hi:[1,0,0]
	v_pk_fma_f32 v[118:119], v[110:111], v[34:35], v[118:119] op_sel_hi:[0,1,1] neg_lo:[1,0,0] neg_hi:[1,0,0]
	v_pk_fma_f32 v[0:1], v[0:1], v[28:29], v[112:113]
	v_pk_fma_f32 v[204:205], v[204:205], v[28:29], v[116:117]
	v_pk_fma_f32 v[2:3], v[2:3], v[30:31], v[114:115]
	v_pk_fma_f32 v[206:207], v[206:207], v[30:31], v[118:119]
	v_pk_fma_f32 v[120:121], v[0:1], v[100:101], 0 op_sel_hi:[1,1,0]
	v_pk_fma_f32 v[122:123], v[204:205], v[100:101], 0 op_sel_hi:[1,1,0]
	v_pk_fma_f32 v[120:121], v[2:3], v[102:103], v[120:121]
	v_pk_fma_f32 v[122:123], v[206:207], v[102:103], v[122:123]
	v_add_f32_e32 v124, v120, v121
	v_add_f32_e32 v125, v122, v123
	s_waitcnt lgkmcnt(0)
; template <int KT>
; __device__ __forceinline__ void scan_block(const Ctx& C, const PV& P, int layer, int sq, int h, int d, int row0, unsigned char* smem) {
;     ...
;             for (int i = 0; i < CH; ++i) {
;                 f32x2 kk2[KT / 2], w2[KT / 2], b2[KT / 2], kd2[KT / 2], r2[KT / 2];
; #pragma unroll
;                 for (int u = 0; u < KT / 4; ++u) {
;                     kk2[2 * u] = (f32x2){nx[0][u][0], nx[0][u][1]}; kk2[2 * u + 1] = (f32x2){nx[0][u][2], nx[0][u][3]};
;                     w2[2 * u] = (f32x2){nx[1][u][0], nx[1][u][1]}; w2[2 * u + 1] = (f32x2){nx[1][u][2], nx[1][u][3]};
;                     b2[2 * u] = (f32x2){nx[2][u][0], nx[2][u][1]}; b2[2 * u + 1] = (f32x2){nx[2][u][2], nx[2][u][3]};
;                     kd2[2 * u] = (f32x2){nx[3][u][0], nx[3][u][1]}; kd2[2 * u + 1] = (f32x2){nx[3][u][2], nx[3][u][3]};
;                     r2[2 * u] = (f32x2){nx[4][u][0], nx[4][u][1]}; r2[2 * u + 1] = (f32x2){nx[4][u][2], nx[4][u][3]};
;                 }
;                 const float vv = nvv;
;                 if (i + 1 < CH) {
; #pragma unroll
;                     for (int u = 0; u < KT / 4; ++u)
; #pragma unroll
;                         for (int a5 = 0; a5 < 5; ++a5) nx[a5][u] = vp0[(i + 1) * 16 + a5 * CH * 16 + u];
;                     nvv = vbuf[(i + 1) * 64 + row];
;                 }
;                 f32x2 acc2 = s[0] * kk2[0];
; #pragma unroll
;                 for (int j = 1; j < KT / 2; ++j) acc2 = __builtin_elementwise_fma(s[j], kk2[j], acc2);
;                 float sa = acc2[0] + acc2[1];
;                 sa += dppf<0xB1>(sa); sa += dppf<0x4E>(sa); sa += dppf<0x141>(sa);
;                 if (TPR == 16) sa += dppf<0x140>(sa);
;                 sa = -sa;
;                 const f32x2 sa2 = (f32x2){sa, sa}, vv2 = (f32x2){vv, vv};
;                 f32x2 y2 = (f32x2){0.f, 0.f};
; #pragma unroll
;                 for (int j = 0; j < KT / 2; ++j) {
;                     s[j] = __builtin_elementwise_fma(s[j], w2[j], __builtin_elementwise_fma(sa2, b2[j], vv2 * kd2[j]));
;                     y2 = __builtin_elementwise_fma(s[j], r2[j], y2);
;                 }
;                 float y = y2[0] + y2[1];
;                 y += dppf<0xB1>(y); y += dppf<0x4E>(y);
;                 yv[i] = y;
;             }
;             if ((q & 3) == 0) {
; #pragma unroll
	v_add_f32_dpp v124, v124, v124 quad_perm:[1,0,3,2] row_mask:0xf bank_mask:0xf bound_ctrl:1
	v_add_f32_dpp v125, v125, v125 quad_perm:[1,0,3,2] row_mask:0xf bank_mask:0xf bound_ctrl:1
	ds_read_b128 v[24:27], v200 offset:3328
	v_add_f32_dpp v124, v124, v124 quad_perm:[2,3,0,1] row_mask:0xf bank_mask:0xf bound_ctrl:1
	v_add_f32_dpp v125, v125, v125 quad_perm:[2,3,0,1] row_mask:0xf bank_mask:0xf bound_ctrl:1
	ds_write2st64_b32 v202, v124, v125 offset0:118 offset1:119
	ds_read_b128 v[48:51], v200 offset:15616
	ds_read_b128 v[32:35], v200 offset:11520
	ds_read_b128 v[28:31], v200 offset:7424
	ds_read_b128 v[100:103], v200 offset:19712
	v_pk_mul_f32 v[104:105], v[0:1], v[4:5]
	v_pk_mul_f32 v[106:107], v[204:205], v[4:5]
	v_pk_fma_f32 v[104:105], v[2:3], v[6:7], v[104:105]
	v_pk_fma_f32 v[106:107], v[206:207], v[6:7], v[106:107]
	v_add_f32_e32 v108, v104, v105
	v_add_f32_e32 v110, v106, v107
	v_pk_mul_f32 v[112:113], v[16:17], v[186:187] op_sel_hi:[1,0]
	v_add_f32_dpp v108, v108, v108 quad_perm:[1,0,3,2] row_mask:0xf bank_mask:0xf bound_ctrl:1
	v_add_f32_dpp v110, v110, v110 quad_perm:[1,0,3,2] row_mask:0xf bank_mask:0xf bound_ctrl:1
	v_pk_mul_f32 v[116:117], v[16:17], v[190:191] op_sel_hi:[1,0]
	v_add_f32_dpp v108, v108, v108 quad_perm:[2,3,0,1] row_mask:0xf bank_mask:0xf bound_ctrl:1
	v_add_f32_dpp v110, v110, v110 quad_perm:[2,3,0,1] row_mask:0xf bank_mask:0xf bound_ctrl:1
	v_pk_mul_f32 v[114:115], v[18:19], v[186:187] op_sel_hi:[1,0]
	v_add_f32_dpp v108, v108, v108 row_half_mirror row_mask:0xf bank_mask:0xf bound_ctrl:1
	v_add_f32_dpp v110, v110, v110 row_half_mirror row_mask:0xf bank_mask:0xf bound_ctrl:1
	v_pk_mul_f32 v[118:119], v[18:19], v[190:191] op_sel_hi:[1,0]
	v_add_f32_dpp v108, v108, v108 row_mirror row_mask:0xf bank_mask:0xf bound_ctrl:1
	v_add_f32_dpp v110, v110, v110 row_mirror row_mask:0xf bank_mask:0xf bound_ctrl:1
	v_pk_fma_f32 v[112:113], v[108:109], v[12:13], v[112:113] op_sel_hi:[0,1,1] neg_lo:[1,0,0] neg_hi:[1,0,0]
	v_pk_fma_f32 v[116:117], v[110:111], v[12:13], v[116:117] op_sel_hi:[0,1,1] neg_lo:[1,0,0] neg_hi:[1,0,0]
	v_pk_fma_f32 v[114:115], v[108:109], v[14:15], v[114:115] op_sel_hi:[0,1,1] neg_lo:[1,0,0] neg_hi:[1,0,0]
	v_pk_fma_f32 v[118:119], v[110:111], v[14:15], v[118:119] op_sel_hi:[0,1,1] neg_lo:[1,0,0] neg_hi:[1,0,0]
	v_pk_fma_f32 v[0:1], v[0:1], v[8:9], v[112:113]
	v_pk_fma_f32 v[204:205], v[204:205], v[8:9], v[116:117]
	v_pk_fma_f32 v[2:3], v[2:3], v[10:11], v[114:115]
	v_pk_fma_f32 v[206:207], v[206:207], v[10:11], v[118:119]
	v_pk_fma_f32 v[120:121], v[0:1], v[20:21], 0 op_sel_hi:[1,1,0]
	v_pk_fma_f32 v[122:123], v[204:205], v[20:21], 0 op_sel_hi:[1,1,0]
	v_pk_fma_f32 v[120:121], v[2:3], v[22:23], v[120:121]
	v_pk_fma_f32 v[122:123], v[206:207], v[22:23], v[122:123]
	v_add_f32_e32 v124, v120, v121
	v_add_f32_e32 v125, v122, v123
	s_waitcnt lgkmcnt(0)
	v_add_f32_dpp v124, v124, v124 quad_perm:[1,0,3,2] row_mask:0xf bank_mask:0xf bound_ctrl:1
	v_add_f32_dpp v125, v125, v125 quad_perm:[1,0,3,2] row_mask:0xf bank_mask:0xf bound_ctrl:1
	ds_read2st64_b32 v[188:189], v201 offset0:94 offset1:95
	v_add_f32_dpp v124, v124, v124 quad_perm:[2,3,0,1] row_mask:0xf bank_mask:0xf bound_ctrl:1
	v_add_f32_dpp v125, v125, v125 quad_perm:[2,3,0,1] row_mask:0xf bank_mask:0xf bound_ctrl:1
	ds_write2st64_b32 v202, v124, v125 offset0:120 offset1:121
	ds_read2st64_b32 v[192:193], v203 offset0:94 offset1:95
	ds_read_b128 v[4:7], v200 offset:3584
	ds_read_b128 v[16:19], v200 offset:15872
	ds_read_b128 v[12:15], v200 offset:11776
	ds_read_b128 v[8:11], v200 offset:7680
	ds_read_b128 v[20:23], v200 offset:19968
	v_pk_mul_f32 v[104:105], v[0:1], v[24:25]
	v_pk_mul_f32 v[106:107], v[204:205], v[24:25]
	v_pk_fma_f32 v[104:105], v[2:3], v[26:27], v[104:105]
	v_pk_fma_f32 v[106:107], v[206:207], v[26:27], v[106:107]
	v_add_f32_e32 v108, v104, v105
	v_add_f32_e32 v110, v106, v107
	v_pk_mul_f32 v[112:113], v[48:49], v[186:187] op_sel:[0,1] op_sel_hi:[1,1]
	v_add_f32_dpp v108, v108, v108 quad_perm:[1,0,3,2] row_mask:0xf bank_mask:0xf bound_ctrl:1
	v_add_f32_dpp v110, v110, v110 quad_perm:[1,0,3,2] row_mask:0xf bank_mask:0xf bound_ctrl:1
	v_pk_mul_f32 v[116:117], v[48:49], v[190:191] op_sel:[0,1] op_sel_hi:[1,1]
	v_add_f32_dpp v108, v108, v108 quad_perm:[2,3,0,1] row_mask:0xf bank_mask:0xf bound_ctrl:1
	v_add_f32_dpp v110, v110, v110 quad_perm:[2,3,0,1] row_mask:0xf bank_mask:0xf bound_ctrl:1
	v_pk_mul_f32 v[114:115], v[50:51], v[186:187] op_sel:[0,1] op_sel_hi:[1,1]
	v_add_f32_dpp v108, v108, v108 row_half_mirror row_mask:0xf bank_mask:0xf bound_ctrl:1
	v_add_f32_dpp v110, v110, v110 row_half_mirror row_mask:0xf bank_mask:0xf bound_ctrl:1
	v_pk_mul_f32 v[118:119], v[50:51], v[190:191] op_sel:[0,1] op_sel_hi:[1,1]
	v_add_f32_dpp v108, v108, v108 row_mirror row_mask:0xf bank_mask:0xf bound_ctrl:1
	v_add_f32_dpp v110, v110, v110 row_mirror row_mask:0xf bank_mask:0xf bound_ctrl:1
	v_pk_fma_f32 v[112:113], v[108:109], v[32:33], v[112:113] op_sel_hi:[0,1,1] neg_lo:[1,0,0] neg_hi:[1,0,0]
	v_pk_fma_f32 v[116:117], v[110:111], v[32:33], v[116:117] op_sel_hi:[0,1,1] neg_lo:[1,0,0] neg_hi:[1,0,0]
	v_pk_fma_f32 v[114:115], v[108:109], v[34:35], v[114:115] op_sel_hi:[0,1,1] neg_lo:[1,0,0] neg_hi:[1,0,0]
	v_pk_fma_f32 v[118:119], v[110:111], v[34:35], v[118:119] op_sel_hi:[0,1,1] neg_lo:[1,0,0] neg_hi:[1,0,0]
	v_pk_fma_f32 v[0:1], v[0:1], v[28:29], v[112:113]
	v_pk_fma_f32 v[204:205], v[204:205], v[28:29], v[116:117]
	v_pk_fma_f32 v[2:3], v[2:3], v[30:31], v[114:115]
	v_pk_fma_f32 v[206:207], v[206:207], v[30:31], v[118:119]
	v_pk_fma_f32 v[120:121], v[0:1], v[100:101], 0 op_sel_hi:[1,1,0]
	v_pk_fma_f32 v[122:123], v[204:205], v[100:101], 0 op_sel_hi:[1,1,0]
	v_pk_fma_f32 v[120:121], v[2:3], v[102:103], v[120:121]
	v_pk_fma_f32 v[122:123], v[206:207], v[102:103], v[122:123]
	v_add_f32_e32 v124, v120, v121
	v_add_f32_e32 v125, v122, v123
	s_waitcnt lgkmcnt(0)
; template <int KT>
; __device__ __forceinline__ void scan_block(const Ctx& C, const PV& P, int layer, int sq, int h, int d, int row0, unsigned char* smem) {
;     ...
;             for (int i = 0; i < CH; ++i) {
;                 f32x2 kk2[KT / 2], w2[KT / 2], b2[KT / 2], kd2[KT / 2], r2[KT / 2];
; #pragma unroll
;                 for (int u = 0; u < KT / 4; ++u) {
;                     kk2[2 * u] = (f32x2){nx[0][u][0], nx[0][u][1]}; kk2[2 * u + 1] = (f32x2){nx[0][u][2], nx[0][u][3]};
;                     w2[2 * u] = (f32x2){nx[1][u][0], nx[1][u][1]}; w2[2 * u + 1] = (f32x2){nx[1][u][2], nx[1][u][3]};
;                     b2[2 * u] = (f32x2){nx[2][u][0], nx[2][u][1]}; b2[2 * u + 1] = (f32x2){nx[2][u][2], nx[2][u][3]};
;                     kd2[2 * u] = (f32x2){nx[3][u][0], nx[3][u][1]}; kd2[2 * u + 1] = (f32x2){nx[3][u][2], nx[3][u][3]};
;                     r2[2 * u] = (f32x2){nx[4][u][0], nx[4][u][1]}; r2[2 * u + 1] = (f32x2){nx[4][u][2], nx[4][u][3]};
;                 }
;                 const float vv = nvv;
;                 if (i + 1 < CH) {
; #pragma unroll
;                     for (int u = 0; u < KT / 4; ++u)
; #pragma unroll
;                         for (int a5 = 0; a5 < 5; ++a5) nx[a5][u] = vp0[(i + 1) * 16 + a5 * CH * 16 + u];
;                     nvv = vbuf[(i + 1) * 64 + row];
;                 }
;                 f32x2 acc2 = s[0] * kk2[0];
; #pragma unroll
;                 for (int j = 1; j < KT / 2; ++j) acc2 = __builtin_elementwise_fma(s[j], kk2[j], acc2);
;                 float sa = acc2[0] + acc2[1];
;                 sa += dppf<0xB1>(sa); sa += dppf<0x4E>(sa); sa += dppf<0x141>(sa);
;                 if (TPR == 16) sa += dppf<0x140>(sa);
;                 sa = -sa;
;                 const f32x2 sa2 = (f32x2){sa, sa}, vv2 = (f32x2){vv, vv};
;                 f32x2 y2 = (f32x2){0.f, 0.f};
; #pragma unroll
;                 for (int j = 0; j < KT / 2; ++j) {
;                     s[j] = __builtin_elementwise_fma(s[j], w2[j], __builtin_elementwise_fma(sa2, b2[j], vv2 * kd2[j]));
;                     y2 = __builtin_elementwise_fma(s[j], r2[j], y2);
;                 }
;                 float y = y2[0] + y2[1];
;                 y += dppf<0xB1>(y); y += dppf<0x4E>(y);
;                 yv[i] = y;
;             }
;             if ((q & 3) == 0) {
; #pragma unroll
	v_add_f32_dpp v124, v124, v124 quad_perm:[1,0,3,2] row_mask:0xf bank_mask:0xf bound_ctrl:1
	v_add_f32_dpp v125, v125, v125 quad_perm:[1,0,3,2] row_mask:0xf bank_mask:0xf bound_ctrl:1
	ds_read_b128 v[24:27], v200 offset:3840
	v_add_f32_dpp v124, v124, v124 quad_perm:[2,3,0,1] row_mask:0xf bank_mask:0xf bound_ctrl:1
	v_add_f32_dpp v125, v125, v125 quad_perm:[2,3,0,1] row_mask:0xf bank_mask:0xf bound_ctrl:1
	ds_write2st64_b32 v202, v124, v125 offset0:122 offset1:123
	ds_read_b128 v[48:51], v200 offset:16128
	ds_read_b128 v[32:35], v200 offset:12032
	ds_read_b128 v[28:31], v200 offset:7936
	ds_read_b128 v[100:103], v200 offset:20224
	v_pk_mul_f32 v[104:105], v[0:1], v[4:5]
	v_pk_mul_f32 v[106:107], v[204:205], v[4:5]
	v_pk_fma_f32 v[104:105], v[2:3], v[6:7], v[104:105]
	v_pk_fma_f32 v[106:107], v[206:207], v[6:7], v[106:107]
	v_add_f32_e32 v108, v104, v105
	v_add_f32_e32 v110, v106, v107
	v_pk_mul_f32 v[112:113], v[16:17], v[188:189] op_sel_hi:[1,0]
	v_add_f32_dpp v108, v108, v108 quad_perm:[1,0,3,2] row_mask:0xf bank_mask:0xf bound_ctrl:1
	v_add_f32_dpp v110, v110, v110 quad_perm:[1,0,3,2] row_mask:0xf bank_mask:0xf bound_ctrl:1
	v_pk_mul_f32 v[116:117], v[16:17], v[192:193] op_sel_hi:[1,0]
	v_add_f32_dpp v108, v108, v108 quad_perm:[2,3,0,1] row_mask:0xf bank_mask:0xf bound_ctrl:1
	v_add_f32_dpp v110, v110, v110 quad_perm:[2,3,0,1] row_mask:0xf bank_mask:0xf bound_ctrl:1
	v_pk_mul_f32 v[114:115], v[18:19], v[188:189] op_sel_hi:[1,0]
	v_add_f32_dpp v108, v108, v108 row_half_mirror row_mask:0xf bank_mask:0xf bound_ctrl:1
	v_add_f32_dpp v110, v110, v110 row_half_mirror row_mask:0xf bank_mask:0xf bound_ctrl:1
	v_pk_mul_f32 v[118:119], v[18:19], v[192:193] op_sel_hi:[1,0]
	v_add_f32_dpp v108, v108, v108 row_mirror row_mask:0xf bank_mask:0xf bound_ctrl:1
	v_add_f32_dpp v110, v110, v110 row_mirror row_mask:0xf bank_mask:0xf bound_ctrl:1
	v_pk_fma_f32 v[112:113], v[108:109], v[12:13], v[112:113] op_sel_hi:[0,1,1] neg_lo:[1,0,0] neg_hi:[1,0,0]
	v_pk_fma_f32 v[116:117], v[110:111], v[12:13], v[116:117] op_sel_hi:[0,1,1] neg_lo:[1,0,0] neg_hi:[1,0,0]
	v_pk_fma_f32 v[114:115], v[108:109], v[14:15], v[114:115] op_sel_hi:[0,1,1] neg_lo:[1,0,0] neg_hi:[1,0,0]
	v_pk_fma_f32 v[118:119], v[110:111], v[14:15], v[118:119] op_sel_hi:[0,1,1] neg_lo:[1,0,0] neg_hi:[1,0,0]
	v_pk_fma_f32 v[0:1], v[0:1], v[8:9], v[112:113]
	v_pk_fma_f32 v[204:205], v[204:205], v[8:9], v[116:117]
	v_pk_fma_f32 v[2:3], v[2:3], v[10:11], v[114:115]
	v_pk_fma_f32 v[206:207], v[206:207], v[10:11], v[118:119]
	v_pk_fma_f32 v[120:121], v[0:1], v[20:21], 0 op_sel_hi:[1,1,0]
	v_pk_fma_f32 v[122:123], v[204:205], v[20:21], 0 op_sel_hi:[1,1,0]
	v_pk_fma_f32 v[120:121], v[2:3], v[22:23], v[120:121]
	v_pk_fma_f32 v[122:123], v[206:207], v[22:23], v[122:123]
	v_add_f32_e32 v124, v120, v121
	v_add_f32_e32 v125, v122, v123
	s_waitcnt lgkmcnt(0)
	v_add_f32_dpp v124, v124, v124 quad_perm:[1,0,3,2] row_mask:0xf bank_mask:0xf bound_ctrl:1
	v_add_f32_dpp v125, v125, v125 quad_perm:[1,0,3,2] row_mask:0xf bank_mask:0xf bound_ctrl:1
	s_nop 0
	v_add_f32_dpp v124, v124, v124 quad_perm:[2,3,0,1] row_mask:0xf bank_mask:0xf bound_ctrl:1
	v_add_f32_dpp v125, v125, v125 quad_perm:[2,3,0,1] row_mask:0xf bank_mask:0xf bound_ctrl:1
	ds_write2st64_b32 v202, v124, v125 offset0:124 offset1:125
	v_pk_mul_f32 v[104:105], v[0:1], v[24:25]
	v_pk_mul_f32 v[106:107], v[204:205], v[24:25]
	v_pk_fma_f32 v[104:105], v[2:3], v[26:27], v[104:105]
	v_pk_fma_f32 v[106:107], v[206:207], v[26:27], v[106:107]
	v_add_f32_e32 v108, v104, v105
	v_add_f32_e32 v110, v106, v107
	v_pk_mul_f32 v[112:113], v[48:49], v[188:189] op_sel:[0,1] op_sel_hi:[1,1]
	v_add_f32_dpp v108, v108, v108 quad_perm:[1,0,3,2] row_mask:0xf bank_mask:0xf bound_ctrl:1
	v_add_f32_dpp v110, v110, v110 quad_perm:[1,0,3,2] row_mask:0xf bank_mask:0xf bound_ctrl:1
	v_pk_mul_f32 v[116:117], v[48:49], v[192:193] op_sel:[0,1] op_sel_hi:[1,1]
	v_add_f32_dpp v108, v108, v108 quad_perm:[2,3,0,1] row_mask:0xf bank_mask:0xf bound_ctrl:1
	v_add_f32_dpp v110, v110, v110 quad_perm:[2,3,0,1] row_mask:0xf bank_mask:0xf bound_ctrl:1
	v_pk_mul_f32 v[114:115], v[50:51], v[188:189] op_sel:[0,1] op_sel_hi:[1,1]
	v_add_f32_dpp v108, v108, v108 row_half_mirror row_mask:0xf bank_mask:0xf bound_ctrl:1
	v_add_f32_dpp v110, v110, v110 row_half_mirror row_mask:0xf bank_mask:0xf bound_ctrl:1
	v_pk_mul_f32 v[118:119], v[50:51], v[192:193] op_sel:[0,1] op_sel_hi:[1,1]
	v_add_f32_dpp v108, v108, v108 row_mirror row_mask:0xf bank_mask:0xf bound_ctrl:1
	v_add_f32_dpp v110, v110, v110 row_mirror row_mask:0xf bank_mask:0xf bound_ctrl:1
	v_pk_fma_f32 v[112:113], v[108:109], v[32:33], v[112:113] op_sel_hi:[0,1,1] neg_lo:[1,0,0] neg_hi:[1,0,0]
	v_pk_fma_f32 v[116:117], v[110:111], v[32:33], v[116:117] op_sel_hi:[0,1,1] neg_lo:[1,0,0] neg_hi:[1,0,0]
	v_pk_fma_f32 v[114:115], v[108:109], v[34:35], v[114:115] op_sel_hi:[0,1,1] neg_lo:[1,0,0] neg_hi:[1,0,0]
	v_pk_fma_f32 v[118:119], v[110:111], v[34:35], v[118:119] op_sel_hi:[0,1,1] neg_lo:[1,0,0] neg_hi:[1,0,0]
	v_pk_fma_f32 v[0:1], v[0:1], v[28:29], v[112:113]
	v_pk_fma_f32 v[204:205], v[204:205], v[28:29], v[116:117]
	v_pk_fma_f32 v[2:3], v[2:3], v[30:31], v[114:115]
	v_pk_fma_f32 v[206:207], v[206:207], v[30:31], v[118:119]
	v_pk_fma_f32 v[120:121], v[0:1], v[100:101], 0 op_sel_hi:[1,1,0]
	v_pk_fma_f32 v[122:123], v[204:205], v[100:101], 0 op_sel_hi:[1,1,0]
	v_pk_fma_f32 v[120:121], v[2:3], v[102:103], v[120:121]
	v_pk_fma_f32 v[122:123], v[206:207], v[102:103], v[122:123]
	v_add_f32_e32 v124, v120, v121
	v_add_f32_e32 v125, v122, v123
	s_nop 0
	v_add_f32_dpp v124, v124, v124 quad_perm:[1,0,3,2] row_mask:0xf bank_mask:0xf bound_ctrl:1
	v_add_f32_dpp v125, v125, v125 quad_perm:[1,0,3,2] row_mask:0xf bank_mask:0xf bound_ctrl:1
	s_nop 0
	v_add_f32_dpp v124, v124, v124 quad_perm:[2,3,0,1] row_mask:0xf bank_mask:0xf bound_ctrl:1
	v_add_f32_dpp v125, v125, v125 quad_perm:[2,3,0,1] row_mask:0xf bank_mask:0xf bound_ctrl:1
	ds_write2st64_b32 v202, v124, v125 offset0:126 offset1:127
; template <int KT>
; __device__ __forceinline__ void scan_block(const Ctx& C, const PV& P, int layer, int sq, int h, int d, int row0, unsigned char* smem) {
;     ...
;     auto stage = [&](int c0, unsigned char* buf) {
;         float* vec = (float*)buf; float* vbuf = (float*)(buf + 20480);
; #pragma unroll
;         for (int j = 0; j < 2; ++j) {
;             const int i = (tid >> 6) + 8 * j, tstep = c0 + i, t = d == 0 ? tstep : S - 1 - tstep;
;             const float rm = t > 0 ? (float)pr_[j][0] : 0.f, rp = t < S - 1 ? (float)pr_[j][2] : 0.f, km = t > 0 ? (float)pk_[j][0] : 0.f, kp = t < S - 1 ? (float)pk_[j][2] : 0.f;
;             const float r1 = (float)pr_[j][1], k1 = (float)pk_[j][1];
;             const float r = r1 + (0.5f * (rm + rp) - r1) * mu_r;
;             const float k = k1 + (0.5f * (km + kp) - k1) * mu_k;
;             const float kk = k * kkw * pn_[j], a = (float)pa_[j];
;             vec[(0 * CH + i) * 64 + ch] = kk;
;             vec[(1 * CH + i) * 64 + ch] = (float)pw_[j];
;             vec[(2 * CH + i) * 64 + ch] = kk * a;
;             vec[(3 * CH + i) * 64 + ch] = k * (1.0f + (a - 1.0f) * kaw);
;             vec[(4 * CH + i) * 64 + ch] = r;
;         }
; #pragma unroll
;         for (int j = 0; j < NV; ++j) {
;             const int i = (ROWS == 32) ? (tid >> 5) : ((tid >> 6) + 8 * j), tstep = c0 + i, t = d == 0 ? tstep : S - 1 - tstep;
;             const float vm = t > 0 ? (float)pv_[j][0] : 0.f, vp = t < S - 1 ? (float)pv_[j][2] : 0.f, v1 = (float)pv_[j][1];
;             vbuf[i * 64 + vr] = v1 + (0.5f * (vm + vp) - v1) * mu_v;
;         }
.Lsc4_skip:
.LBB0_549:
	s_or_b64 exec, exec, s[20:21]
	s_mov_b64 s[20:21], -1
	s_and_b64 vcc, exec, s[12:13]
	v_add_u32_e32 v4, s4, v67
	s_cbranch_vccz .LBB0_551
	s_waitcnt vmcnt(20)
	v_cvt_f32_f16_e32 v5, v60
	s_waitcnt vmcnt(18)
	v_cvt_f32_f16_e32 v7, v62
	s_waitcnt vmcnt(17)
	v_cvt_f32_f16_e32 v8, v65
	s_waitcnt vmcnt(15)
	v_cvt_f32_f16_e32 v9, v63
	v_cndmask_b32_e64 v6, v95, v96, s[40:41]
	v_cmp_lt_i32_e32 vcc, 0, v6
	v_cmp_gt_i32_e64 s[44:45], s18, v6
	s_and_b32 s7, s5, 0x8000
	v_cndmask_b32_e32 v5, 0, v5, vcc
	v_cndmask_b32_e64 v6, 0, v7, s[44:45]
	v_cndmask_b32_e32 v7, 0, v8, vcc
	v_cndmask_b32_e64 v8, 0, v9, s[44:45]
	v_add_f32_e32 v5, v5, v6
	v_add_f32_e32 v6, v7, v8
	v_fma_mix_f32 v6, v6, s38, -v64 op_sel_hi:[0,0,1]
	s_waitcnt vmcnt(14)
	v_cvt_f32_f16_e32 v8, v66
	v_fma_mix_f32 v6, v55, v6, v64 op_sel_hi:[0,0,1]
	s_waitcnt vmcnt(13)
	v_cvt_f32_f16_e32 v10, v68
	s_add_i32 s7, s7, 0
	v_mul_f32_e32 v7, v56, v6
	s_waitcnt vmcnt(12)
	v_mul_f32_e32 v7, v73, v7
	v_lshl_add_u32 v9, v144, 2, s7
	ds_write_b32 v9, v7
	v_lshl_add_u32 v9, v74, 2, s7
	v_mul_f32_e32 v7, v7, v8
	ds_write2st64_b32 v9, v10, v7 offset0:16 offset1:32
	v_add_f32_e32 v7, -1.0, v8
	v_fma_f32 v7, v57, v7, 1.0
	v_fma_mix_f32 v5, v5, s38, -v61 op_sel_hi:[0,0,1]
	v_mul_f32_e32 v6, v7, v6
	s_waitcnt vmcnt(11)
	v_cvt_f32_f16_e32 v7, v75
	v_fma_mix_f32 v5, v54, v5, v61 op_sel_hi:[0,0,1]
	ds_write2st64_b32 v9, v6, v5 offset0:48 offset1:64
	v_cndmask_b32_e64 v5, v88, v94, s[40:41]
	v_cmp_lt_i32_e32 vcc, 0, v5
	s_waitcnt vmcnt(8)
	v_cvt_f32_f16_e32 v8, v81
	s_waitcnt vmcnt(6)
	v_cvt_f32_f16_e32 v9, v79
	v_cndmask_b32_e32 v6, 0, v7, vcc
	v_cvt_f32_f16_e32 v7, v76
	v_cmp_gt_i32_e64 s[44:45], s18, v5
	v_lshl_add_u32 v10, v78, 2, s7
	s_mov_b64 s[20:21], 0
	v_cndmask_b32_e64 v5, 0, v7, s[44:45]
	v_cndmask_b32_e32 v7, 0, v8, vcc
	v_cndmask_b32_e64 v8, 0, v9, s[44:45]
	v_add_f32_e32 v5, v6, v5
	v_add_f32_e32 v6, v7, v8
	v_fma_mix_f32 v6, v6, s38, -v80 op_sel_hi:[0,0,1]
	s_waitcnt vmcnt(3)
	v_cvt_f32_f16_e32 v8, v86
	v_fma_mix_f32 v6, v55, v6, v80 op_sel_hi:[0,0,1]
	v_cvt_f32_f16_e32 v9, v87
	v_mul_f32_e32 v7, v56, v6
	v_mul_f32_e32 v7, v89, v7
	ds_write_b32 v10, v7
	v_mul_f32_e32 v7, v7, v8
	ds_write2st64_b32 v10, v9, v7 offset0:16 offset1:32
	v_add_f32_e32 v7, -1.0, v8
	v_fma_mix_f32 v5, v5, s38, -v77 op_sel_hi:[0,0,1]
	v_fma_f32 v7, v57, v7, 1.0
	v_fma_mix_f32 v5, v54, v5, v77 op_sel_hi:[0,0,1]
	v_mul_f32_e32 v6, v7, v6
	ds_write2st64_b32 v10, v6, v5 offset0:48 offset1:64
	v_add_u32_e32 v6, s4, v67
	s_waitcnt vmcnt(2)
	v_cvt_f32_f16_e32 v8, v90
	v_add_u32_e32 v7, 16, v6
	v_add_u32_e32 v5, -16, v69
	s_waitcnt vmcnt(0)
	v_cvt_f32_f16_e32 v9, v92
	v_cndmask_b32_e64 v7, v5, v7, s[40:41]
	v_cmp_lt_i32_e32 vcc, 0, v7
	s_nop 1
	v_cndmask_b32_e32 v8, 0, v8, vcc
	v_cmp_gt_i32_e32 vcc, s18, v7
	s_nop 1
	v_cndmask_b32_e32 v7, 0, v9, vcc
	v_add_f32_e32 v7, v7, v8
	v_fma_mix_f32 v7, v7, s38, -v91 op_sel_hi:[0,0,1]
	v_lshl_add_u32 v9, v82, 2, s7
	v_fma_mix_f32 v7, v58, v7, v91 op_sel_hi:[0,0,1]
	ds_write_b32 v9, v7 offset:20480
